# mem-sample item: second 16-load K/V batch issued right after the first into free VGPRs (deep prefetch), copied back before its conversion
# baseline (speedup 1.0000x reference)
.LBB0_687:
	s_andn2_b64 vcc, exec, s[0:1]
	s_cbranch_vccnz .LBB0_693
	v_lshrrev_b32_e32 v78, 2, v38
	s_and_b32 s33, s92, 3
	v_lshlrev_b64 v[0:1], 10, v[78:79]
	v_or_b32_e32 v0, s33, v0
	v_or_b32_e32 v2, v0, v94
	v_mov_b32_e32 v3, v1
	v_or_b32_e32 v18, v0, v96
	v_mov_b32_e32 v19, v1
	v_or_b32_e32 v34, v0, v98
	v_mov_b32_e32 v35, v1
	v_or_b32_e32 v52, v0, v100
	v_mov_b32_e32 v53, v1
	v_lshlrev_b64 v[10:11], 9, v[2:3]
	v_lshlrev_b32_e32 v39, 2, v86
	v_readlane_b32 s4, v254, 3
	v_lshlrev_b64 v[26:27], 9, v[18:19]
	v_lshlrev_b64 v[44:45], 9, v[34:35]
	v_lshlrev_b64 v[60:61], 9, v[52:53]
	v_or_b32_e32 v10, v10, v39
	v_readlane_b32 s16, v254, 15
	v_readlane_b32 s17, v254, 16
	v_readlane_b32 s18, v254, 17
	v_readlane_b32 s19, v254, 18
	v_or_b32_e32 v26, v26, v39
	v_or_b32_e32 v44, v44, v39
	v_or_b32_e32 v60, v60, v39
	v_lshl_add_u64 v[6:7], s[16:17], 0, v[10:11]
	v_lshl_add_u64 v[14:15], s[18:19], 0, v[10:11]
	v_lshl_add_u64 v[22:23], s[16:17], 0, v[26:27]
	v_lshl_add_u64 v[30:31], s[18:19], 0, v[26:27]
	s_waitcnt vmcnt(2)
	v_lshl_add_u64 v[40:41], s[16:17], 0, v[44:45]
	v_lshl_add_u64 v[48:49], s[18:19], 0, v[44:45]
	v_lshl_add_u64 v[56:57], s[16:17], 0, v[60:61]
	v_lshl_add_u64 v[64:65], s[18:19], 0, v[60:61]
	global_load_dwordx4 v[2:5], v[6:7], off offset:16
	s_nop 0
	global_load_dwordx4 v[6:9], v[6:7], off
	s_nop 0
	global_load_dwordx4 v[10:13], v[14:15], off offset:16
	s_nop 0
	global_load_dwordx4 v[14:17], v[14:15], off
	s_nop 0
	global_load_dwordx4 v[18:21], v[22:23], off offset:16
	s_nop 0
	global_load_dwordx4 v[22:25], v[22:23], off
	s_nop 0
	global_load_dwordx4 v[26:29], v[30:31], off offset:16
	s_nop 0
	global_load_dwordx4 v[30:33], v[30:31], off
	s_nop 0
	global_load_dwordx4 v[34:37], v[40:41], off offset:16
	s_nop 0
	global_load_dwordx4 v[40:43], v[40:41], off
	s_nop 0
	global_load_dwordx4 v[44:47], v[48:49], off offset:16
	s_nop 0
	global_load_dwordx4 v[48:51], v[48:49], off
	s_nop 0
	global_load_dwordx4 v[52:55], v[56:57], off offset:16
	s_nop 0
	global_load_dwordx4 v[56:59], v[56:57], off
	s_nop 0
	global_load_dwordx4 v[60:63], v[64:65], off offset:16
	s_nop 0
	global_load_dwordx4 v[64:67], v[64:65], off
	v_or_b32_e32 v70, v0, v102
	v_mov_b32_e32 v71, v1
	v_or_b32_e32 v138, v0, v104
	v_mov_b32_e32 v139, v1
	v_or_b32_e32 v220, v0, v106
	v_mov_b32_e32 v221, v1
	v_lshl_add_u64 v[74:75], v[0:1], 0, v[108:109]
	v_lshlrev_b64 v[130:131], 9, v[70:71]
	v_lshlrev_b64 v[212:213], 9, v[138:139]
	v_lshlrev_b64 v[228:229], 9, v[220:221]
	v_lshlrev_b64 v[74:75], 9, v[74:75]
	v_or_b32_e32 v130, v130, v39
	v_or_b32_e32 v212, v212, v39
	v_or_b32_e32 v228, v228, v39
	v_or_b32_e32 v74, v74, v39
	v_lshl_add_u64 v[82:83], s[16:17], 0, v[130:131]
	v_lshl_add_u64 v[134:135], s[18:19], 0, v[130:131]
	v_lshl_add_u64 v[142:143], s[16:17], 0, v[212:213]
	v_lshl_add_u64 v[216:217], s[18:19], 0, v[212:213]
	v_lshl_add_u64 v[224:225], s[16:17], 0, v[228:229]
	v_lshl_add_u64 v[232:233], s[18:19], 0, v[228:229]
	v_lshl_add_u64 v[240:241], s[16:17], 0, v[74:75]
	v_lshl_add_u64 v[74:75], s[18:19], 0, v[74:75]
	global_load_dwordx4 v[70:73], v[82:83], off offset:16
	s_nop 0
	global_load_dwordx4 v[82:85], v[82:83], off
	s_nop 0
	global_load_dwordx4 v[130:133], v[134:135], off offset:16
	s_nop 0
	global_load_dwordx4 v[134:137], v[134:135], off
	s_nop 0
	global_load_dwordx4 v[138:141], v[142:143], off offset:16
	s_nop 0
	global_load_dwordx4 v[142:145], v[142:143], off
	s_nop 0
	global_load_dwordx4 v[212:215], v[216:217], off offset:16
	s_nop 0
	global_load_dwordx4 v[216:219], v[216:217], off
	s_nop 0
	global_load_dwordx4 v[220:223], v[224:225], off offset:16
	s_nop 0
	global_load_dwordx4 v[224:227], v[224:225], off
	s_nop 0
	global_load_dwordx4 v[228:231], v[232:233], off offset:16
	s_nop 0
	global_load_dwordx4 v[232:235], v[232:233], off
	s_nop 0
	global_load_dwordx4 v[236:239], v[240:241], off offset:16
	s_nop 0
	global_load_dwordx4 v[240:243], v[240:241], off
	s_nop 0
	global_load_dwordx4 v[244:247], v[74:75], off offset:16
	global_load_dwordx4 v[248:251], v[74:75], off
	v_readlane_b32 s5, v254, 4
	v_readlane_b32 s6, v254, 5
	v_readlane_b32 s7, v254, 6
	v_readlane_b32 s8, v254, 7
	v_readlane_b32 s9, v254, 8
	v_readlane_b32 s10, v254, 9
	v_readlane_b32 s11, v254, 10
	v_readlane_b32 s12, v254, 11
	v_readlane_b32 s13, v254, 12
	v_readlane_b32 s14, v254, 13
	v_readlane_b32 s15, v254, 14
	s_waitcnt vmcnt(30)
	v_bfe_u32 v68, v6, 16, 1
	v_add3_u32 v6, v6, v68, s74
	v_bfe_u32 v68, v7, 16, 1
	v_lshrrev_b32_e32 v6, 16, v6
	v_add3_u32 v7, v7, v68, s74
	v_and_or_b32 v6, v7, s73, v6
	v_bfe_u32 v7, v8, 16, 1
	v_add3_u32 v7, v8, v7, s74
	v_bfe_u32 v8, v9, 16, 1
	v_lshrrev_b32_e32 v7, 16, v7
	v_add3_u32 v8, v9, v8, s74
	v_and_or_b32 v7, v8, s73, v7
	v_bfe_u32 v8, v2, 16, 1
	v_add3_u32 v2, v2, v8, s74
	v_bfe_u32 v8, v3, 16, 1
	v_lshrrev_b32_e32 v2, 16, v2
	v_add3_u32 v3, v3, v8, s74
	v_and_or_b32 v8, v3, s73, v2
	v_bfe_u32 v2, v4, 16, 1
	v_add3_u32 v2, v4, v2, s74
	v_bfe_u32 v3, v5, 16, 1
	v_lshrrev_b32_e32 v2, 16, v2
	v_add3_u32 v3, v5, v3, s74
	v_and_or_b32 v9, v3, s73, v2
	s_waitcnt vmcnt(28)
	v_bfe_u32 v2, v14, 16, 1
	v_add3_u32 v2, v14, v2, s74
	v_bfe_u32 v14, v10, 16, 1
	v_add3_u32 v10, v10, v14, s74
	v_bfe_u32 v14, v11, 16, 1
	v_add3_u32 v11, v11, v14, s74
	v_bfe_u32 v14, v12, 16, 1
	v_add3_u32 v12, v12, v14, s74
	v_bfe_u32 v14, v13, 16, 1
	v_bfe_u32 v3, v15, 16, 1
	v_bfe_u32 v4, v16, 16, 1
	v_bfe_u32 v5, v17, 16, 1
	v_add3_u32 v13, v13, v14, s74
	v_add_u32_e32 v14, v81, v164
	v_add3_u32 v3, v15, v3, s74
	v_add3_u32 v4, v16, v4, s74
	v_add3_u32 v5, v17, v5, s74
	ds_write_b128 v14, v[6:9]
	ds_write_b16_d16_hi v165, v2
	ds_write_b16_d16_hi v165, v3 offset:528
	ds_write_b16_d16_hi v165, v4 offset:1056
	ds_write_b16_d16_hi v165, v5 offset:1584
	ds_write_b16_d16_hi v165, v10 offset:2112
	ds_write_b16_d16_hi v165, v11 offset:2640
	ds_write_b16_d16_hi v165, v12 offset:3168
	ds_write_b16_d16_hi v165, v13 offset:3696
	s_waitcnt vmcnt(26)
	v_bfe_u32 v2, v22, 16, 1
	v_add3_u32 v2, v22, v2, s74
	v_bfe_u32 v3, v23, 16, 1
	v_lshrrev_b32_e32 v2, 16, v2
	v_add3_u32 v3, v23, v3, s74
	v_and_or_b32 v2, v3, s73, v2
	v_bfe_u32 v3, v24, 16, 1
	v_add3_u32 v3, v24, v3, s74
	v_bfe_u32 v4, v25, 16, 1
	v_lshrrev_b32_e32 v3, 16, v3
	v_add3_u32 v4, v25, v4, s74
	v_and_or_b32 v3, v4, s73, v3
	v_bfe_u32 v4, v18, 16, 1
	v_add3_u32 v4, v18, v4, s74
	v_bfe_u32 v5, v19, 16, 1
	v_lshrrev_b32_e32 v4, 16, v4
	v_add3_u32 v5, v19, v5, s74
	v_and_or_b32 v4, v5, s73, v4
	v_bfe_u32 v5, v20, 16, 1
	v_add3_u32 v5, v20, v5, s74
	v_bfe_u32 v6, v21, 16, 1
	v_lshrrev_b32_e32 v5, 16, v5
	v_add3_u32 v6, v21, v6, s74
	v_and_or_b32 v5, v6, s73, v5
	s_waitcnt vmcnt(24)
	v_bfe_u32 v6, v30, 16, 1
	v_bfe_u32 v7, v31, 16, 1
	v_bfe_u32 v8, v32, 16, 1
	v_bfe_u32 v9, v33, 16, 1
	v_bfe_u32 v10, v26, 16, 1
	v_bfe_u32 v11, v27, 16, 1
	v_bfe_u32 v12, v28, 16, 1
	v_bfe_u32 v13, v29, 16, 1
	v_add_u32_e32 v14, v81, v166
	v_add3_u32 v6, v30, v6, s74
	v_add3_u32 v7, v31, v7, s74
	v_add3_u32 v8, v32, v8, s74
	v_add3_u32 v9, v33, v9, s74
	v_add3_u32 v10, v26, v10, s74
	v_add3_u32 v11, v27, v11, s74
	v_add3_u32 v12, v28, v12, s74
	v_add3_u32 v13, v29, v13, s74
	ds_write_b128 v14, v[2:5]
	ds_write_b16_d16_hi v167, v6
	ds_write_b16_d16_hi v167, v7 offset:528
	ds_write_b16_d16_hi v167, v8 offset:1056
	ds_write_b16_d16_hi v167, v9 offset:1584
	ds_write_b16_d16_hi v167, v10 offset:2112
	ds_write_b16_d16_hi v167, v11 offset:2640
	ds_write_b16_d16_hi v167, v12 offset:3168
	ds_write_b16_d16_hi v167, v13 offset:3696
	s_waitcnt vmcnt(22)
	v_bfe_u32 v2, v40, 16, 1
	v_add3_u32 v2, v40, v2, s74
	v_bfe_u32 v3, v41, 16, 1
	v_lshrrev_b32_e32 v2, 16, v2
	v_add3_u32 v3, v41, v3, s74
	v_and_or_b32 v2, v3, s73, v2
	v_bfe_u32 v3, v42, 16, 1
	v_add3_u32 v3, v42, v3, s74
	v_bfe_u32 v4, v43, 16, 1
	v_lshrrev_b32_e32 v3, 16, v3
	v_add3_u32 v4, v43, v4, s74
	v_and_or_b32 v3, v4, s73, v3
	v_bfe_u32 v4, v34, 16, 1
	v_add3_u32 v4, v34, v4, s74
	v_bfe_u32 v5, v35, 16, 1
	v_lshrrev_b32_e32 v4, 16, v4
	v_add3_u32 v5, v35, v5, s74
	v_and_or_b32 v4, v5, s73, v4
	v_bfe_u32 v5, v36, 16, 1
	v_add3_u32 v5, v36, v5, s74
	v_bfe_u32 v6, v37, 16, 1
	v_lshrrev_b32_e32 v5, 16, v5
	v_add3_u32 v6, v37, v6, s74
	v_and_or_b32 v5, v6, s73, v5
	s_waitcnt vmcnt(20)
	v_bfe_u32 v6, v48, 16, 1
	v_bfe_u32 v7, v49, 16, 1
	v_bfe_u32 v8, v50, 16, 1
	v_bfe_u32 v9, v51, 16, 1
	v_bfe_u32 v10, v44, 16, 1
	v_bfe_u32 v11, v45, 16, 1
	v_bfe_u32 v12, v46, 16, 1
	v_bfe_u32 v13, v47, 16, 1
	v_add3_u32 v6, v48, v6, s74
	v_add3_u32 v7, v49, v7, s74
	v_add3_u32 v8, v50, v8, s74
	v_add3_u32 v9, v51, v9, s74
	v_add3_u32 v10, v44, v10, s74
	v_add3_u32 v11, v45, v11, s74
	v_add3_u32 v12, v46, v12, s74
	v_add3_u32 v13, v47, v13, s74
	ds_write_b128 v198, v[2:5]
	ds_write_b16_d16_hi v181, v6
	ds_write_b16_d16_hi v181, v7 offset:528
	ds_write_b16_d16_hi v181, v8 offset:1056
	ds_write_b16_d16_hi v181, v9 offset:1584
	ds_write_b16_d16_hi v181, v10 offset:2112
	ds_write_b16_d16_hi v181, v11 offset:2640
	ds_write_b16_d16_hi v181, v12 offset:3168
	ds_write_b16_d16_hi v181, v13 offset:3696
	s_waitcnt vmcnt(18)
	v_bfe_u32 v2, v56, 16, 1
	v_add3_u32 v2, v56, v2, s74
	v_bfe_u32 v3, v57, 16, 1
	v_lshrrev_b32_e32 v2, 16, v2
	v_add3_u32 v3, v57, v3, s74
	v_and_or_b32 v2, v3, s73, v2
	v_bfe_u32 v3, v58, 16, 1
	v_add3_u32 v3, v58, v3, s74
	v_bfe_u32 v4, v59, 16, 1
	v_lshrrev_b32_e32 v3, 16, v3
	v_add3_u32 v4, v59, v4, s74
	v_and_or_b32 v3, v4, s73, v3
	v_bfe_u32 v4, v52, 16, 1
	v_add3_u32 v4, v52, v4, s74
	v_bfe_u32 v5, v53, 16, 1
	v_lshrrev_b32_e32 v4, 16, v4
	v_add3_u32 v5, v53, v5, s74
	v_and_or_b32 v4, v5, s73, v4
	v_bfe_u32 v5, v54, 16, 1
	v_add3_u32 v5, v54, v5, s74
	v_bfe_u32 v6, v55, 16, 1
	v_lshrrev_b32_e32 v5, 16, v5
	v_add3_u32 v6, v55, v6, s74
	v_and_or_b32 v5, v6, s73, v5
	s_waitcnt vmcnt(16)
	v_bfe_u32 v6, v64, 16, 1
	v_bfe_u32 v7, v65, 16, 1
	v_bfe_u32 v8, v66, 16, 1
	v_bfe_u32 v9, v67, 16, 1
	v_bfe_u32 v10, v60, 16, 1
	v_bfe_u32 v11, v61, 16, 1
	v_bfe_u32 v12, v62, 16, 1
	v_bfe_u32 v13, v63, 16, 1
	v_add_u32_e32 v14, v81, v169
	v_add3_u32 v6, v64, v6, s74
	v_add3_u32 v7, v65, v7, s74
	v_add3_u32 v8, v66, v8, s74
	v_add3_u32 v9, v67, v9, s74
	v_add3_u32 v10, v60, v10, s74
	v_add3_u32 v11, v61, v11, s74
	v_add3_u32 v12, v62, v12, s74
	v_add3_u32 v13, v63, v13, s74
	ds_write_b128 v14, v[2:5]
	ds_write_b16_d16_hi v170, v6
	ds_write_b16_d16_hi v170, v7 offset:528
	ds_write_b16_d16_hi v170, v8 offset:1056
	ds_write_b16_d16_hi v170, v9 offset:1584
	ds_write_b16_d16_hi v170, v10 offset:2112
	ds_write_b16_d16_hi v170, v11 offset:2640
	ds_write_b16_d16_hi v170, v12 offset:3168
	ds_write_b16_d16_hi v170, v13 offset:3696
	s_waitcnt vmcnt(0)
	v_mov_b64_e32 v[2:3], v[70:71]
	v_mov_b64_e32 v[4:5], v[72:73]
	v_mov_b64_e32 v[6:7], v[82:83]
	v_mov_b64_e32 v[8:9], v[84:85]
	v_mov_b64_e32 v[10:11], v[130:131]
	v_mov_b64_e32 v[12:13], v[132:133]
	v_mov_b64_e32 v[14:15], v[134:135]
	v_mov_b64_e32 v[16:17], v[136:137]
	v_mov_b64_e32 v[18:19], v[138:139]
	v_mov_b64_e32 v[20:21], v[140:141]
	v_mov_b64_e32 v[22:23], v[142:143]
	v_mov_b64_e32 v[24:25], v[144:145]
	v_mov_b64_e32 v[26:27], v[212:213]
	v_mov_b64_e32 v[28:29], v[214:215]
	v_mov_b64_e32 v[30:31], v[216:217]
	v_mov_b64_e32 v[32:33], v[218:219]
	v_mov_b64_e32 v[34:35], v[220:221]
	v_mov_b64_e32 v[36:37], v[222:223]
	v_mov_b64_e32 v[40:41], v[224:225]
	v_mov_b64_e32 v[42:43], v[226:227]
	v_mov_b64_e32 v[44:45], v[228:229]
	v_mov_b64_e32 v[46:47], v[230:231]
	v_mov_b64_e32 v[48:49], v[232:233]
	v_mov_b64_e32 v[50:51], v[234:235]
	v_mov_b64_e32 v[52:53], v[236:237]
	v_mov_b64_e32 v[54:55], v[238:239]
	v_mov_b64_e32 v[56:57], v[240:241]
	v_mov_b64_e32 v[58:59], v[242:243]
	v_mov_b64_e32 v[60:61], v[244:245]
	v_mov_b64_e32 v[62:63], v[246:247]
	v_mov_b64_e32 v[64:65], v[248:249]
	v_mov_b64_e32 v[66:67], v[250:251]
	s_waitcnt vmcnt(14)
	v_bfe_u32 v0, v6, 16, 1
	v_add3_u32 v0, v6, v0, s74
	v_bfe_u32 v1, v7, 16, 1
	v_lshrrev_b32_e32 v0, 16, v0
	v_add3_u32 v1, v7, v1, s74
	v_and_or_b32 v0, v1, s73, v0
	v_bfe_u32 v1, v8, 16, 1
	v_add3_u32 v1, v8, v1, s74
	v_bfe_u32 v6, v9, 16, 1
	v_lshrrev_b32_e32 v1, 16, v1
	v_add3_u32 v6, v9, v6, s74
	v_and_or_b32 v1, v6, s73, v1
	v_bfe_u32 v6, v2, 16, 1
	v_add3_u32 v2, v2, v6, s74
	v_bfe_u32 v6, v3, 16, 1
	v_lshrrev_b32_e32 v2, 16, v2
	v_add3_u32 v3, v3, v6, s74
	v_and_or_b32 v2, v3, s73, v2
	v_bfe_u32 v3, v4, 16, 1
	v_add3_u32 v3, v4, v3, s74
	v_bfe_u32 v4, v5, 16, 1
	v_lshrrev_b32_e32 v3, 16, v3
	v_add3_u32 v4, v5, v4, s74
	s_waitcnt vmcnt(13)
	v_bfe_u32 v8, v10, 16, 1
	v_bfe_u32 v9, v11, 16, 1
	v_and_or_b32 v3, v4, s73, v3
	s_waitcnt vmcnt(12)
	v_bfe_u32 v4, v14, 16, 1
	v_bfe_u32 v5, v15, 16, 1
	v_bfe_u32 v6, v16, 16, 1
	v_bfe_u32 v7, v17, 16, 1
	v_add3_u32 v8, v10, v8, s74
	v_add3_u32 v9, v11, v9, s74
	v_bfe_u32 v10, v12, 16, 1
	v_bfe_u32 v11, v13, 16, 1
	v_add3_u32 v4, v14, v4, s74
	v_add3_u32 v5, v15, v5, s74
	v_add3_u32 v6, v16, v6, s74
	v_add3_u32 v7, v17, v7, s74
	v_add3_u32 v10, v12, v10, s74
	v_add3_u32 v11, v13, v11, s74
	ds_write_b128 v199, v[0:3]
	ds_write_b16_d16_hi v182, v4
	ds_write_b16_d16_hi v182, v5 offset:528
	ds_write_b16_d16_hi v182, v6 offset:1056
	ds_write_b16_d16_hi v182, v7 offset:1584
	ds_write_b16_d16_hi v182, v8 offset:2112
	ds_write_b16_d16_hi v182, v9 offset:2640
	ds_write_b16_d16_hi v182, v10 offset:3168
	ds_write_b16_d16_hi v182, v11 offset:3696
	s_waitcnt vmcnt(10)
	v_bfe_u32 v0, v22, 16, 1
	v_add3_u32 v0, v22, v0, s74
	v_bfe_u32 v1, v23, 16, 1
	v_lshrrev_b32_e32 v0, 16, v0
	v_add3_u32 v1, v23, v1, s74
	v_and_or_b32 v0, v1, s73, v0
	v_bfe_u32 v1, v24, 16, 1
	v_add3_u32 v1, v24, v1, s74
	v_bfe_u32 v2, v25, 16, 1
	v_lshrrev_b32_e32 v1, 16, v1
	v_add3_u32 v2, v25, v2, s74
	v_and_or_b32 v1, v2, s73, v1
	v_bfe_u32 v2, v18, 16, 1
	v_add3_u32 v2, v18, v2, s74
	v_bfe_u32 v3, v19, 16, 1
	v_lshrrev_b32_e32 v2, 16, v2
	v_add3_u32 v3, v19, v3, s74
	v_and_or_b32 v2, v3, s73, v2
	v_bfe_u32 v3, v20, 16, 1
	v_add3_u32 v3, v20, v3, s74
	v_bfe_u32 v4, v21, 16, 1
	v_lshrrev_b32_e32 v3, 16, v3
	v_add3_u32 v4, v21, v4, s74
	v_and_or_b32 v3, v4, s73, v3
	s_waitcnt vmcnt(8)
	v_bfe_u32 v4, v30, 16, 1
	v_bfe_u32 v5, v31, 16, 1
	v_bfe_u32 v6, v32, 16, 1
	v_bfe_u32 v7, v33, 16, 1
	v_bfe_u32 v8, v26, 16, 1
	v_bfe_u32 v9, v27, 16, 1
	v_bfe_u32 v10, v28, 16, 1
	v_bfe_u32 v11, v29, 16, 1
	v_add_u32_e32 v12, v81, v172
	v_add3_u32 v4, v30, v4, s74
	v_add3_u32 v5, v31, v5, s74
	v_add3_u32 v6, v32, v6, s74
	v_add3_u32 v7, v33, v7, s74
	v_add3_u32 v8, v26, v8, s74
	v_add3_u32 v9, v27, v9, s74
	v_add3_u32 v10, v28, v10, s74
	v_add3_u32 v11, v29, v11, s74
	ds_write_b128 v12, v[0:3]
	ds_write_b16_d16_hi v173, v4
	ds_write_b16_d16_hi v173, v5 offset:528
	ds_write_b16_d16_hi v173, v6 offset:1056
	ds_write_b16_d16_hi v173, v7 offset:1584
	ds_write_b16_d16_hi v173, v8 offset:2112
	ds_write_b16_d16_hi v173, v9 offset:2640
	ds_write_b16_d16_hi v173, v10 offset:3168
	ds_write_b16_d16_hi v173, v11 offset:3696
	s_waitcnt vmcnt(6)
	v_bfe_u32 v0, v40, 16, 1
	v_add3_u32 v0, v40, v0, s74
	v_bfe_u32 v1, v41, 16, 1
	v_lshrrev_b32_e32 v0, 16, v0
	v_add3_u32 v1, v41, v1, s74
	v_and_or_b32 v0, v1, s73, v0
	v_bfe_u32 v1, v42, 16, 1
	v_add3_u32 v1, v42, v1, s74
	v_bfe_u32 v2, v43, 16, 1
	v_lshrrev_b32_e32 v1, 16, v1
	v_add3_u32 v2, v43, v2, s74
	v_and_or_b32 v1, v2, s73, v1
	v_bfe_u32 v2, v34, 16, 1
	v_add3_u32 v2, v34, v2, s74
	v_bfe_u32 v3, v35, 16, 1
	v_lshrrev_b32_e32 v2, 16, v2
	v_add3_u32 v3, v35, v3, s74
	v_and_or_b32 v2, v3, s73, v2
	v_bfe_u32 v3, v36, 16, 1
	v_add3_u32 v3, v36, v3, s74
	v_bfe_u32 v4, v37, 16, 1
	v_lshrrev_b32_e32 v3, 16, v3
	v_add3_u32 v4, v37, v4, s74
	v_and_or_b32 v3, v4, s73, v3
	s_waitcnt vmcnt(4)
	v_bfe_u32 v4, v48, 16, 1
	v_bfe_u32 v5, v49, 16, 1
	v_bfe_u32 v6, v50, 16, 1
	v_bfe_u32 v7, v51, 16, 1
	v_bfe_u32 v8, v44, 16, 1
	v_bfe_u32 v9, v45, 16, 1
	v_bfe_u32 v10, v46, 16, 1
	v_bfe_u32 v11, v47, 16, 1
	v_add3_u32 v4, v48, v4, s74
	v_add3_u32 v5, v49, v5, s74
	v_add3_u32 v6, v50, v6, s74
	v_add3_u32 v7, v51, v7, s74
	v_add3_u32 v8, v44, v8, s74
	v_add3_u32 v9, v45, v9, s74
	v_add3_u32 v10, v46, v10, s74
	v_add3_u32 v11, v47, v11, s74
	ds_write_b128 v200, v[0:3]
	ds_write_b16_d16_hi v183, v4
	ds_write_b16_d16_hi v183, v5 offset:528
	ds_write_b16_d16_hi v183, v6 offset:1056
	ds_write_b16_d16_hi v183, v7 offset:1584
	ds_write_b16_d16_hi v183, v8 offset:2112
	ds_write_b16_d16_hi v183, v9 offset:2640
	ds_write_b16_d16_hi v183, v10 offset:3168
	ds_write_b16_d16_hi v183, v11 offset:3696
	s_waitcnt vmcnt(2)
	v_bfe_u32 v0, v56, 16, 1
	v_add3_u32 v0, v56, v0, s74
	v_bfe_u32 v1, v57, 16, 1
	v_lshrrev_b32_e32 v0, 16, v0
	v_add3_u32 v1, v57, v1, s74
	v_and_or_b32 v0, v1, s73, v0
	v_bfe_u32 v1, v58, 16, 1
	v_add3_u32 v1, v58, v1, s74
	v_bfe_u32 v2, v59, 16, 1
	v_lshrrev_b32_e32 v1, 16, v1
	v_add3_u32 v2, v59, v2, s74
	v_and_or_b32 v1, v2, s73, v1
	v_bfe_u32 v2, v52, 16, 1
	v_add3_u32 v2, v52, v2, s74
	v_bfe_u32 v3, v53, 16, 1
	v_lshrrev_b32_e32 v2, 16, v2
	v_add3_u32 v3, v53, v3, s74
	v_and_or_b32 v2, v3, s73, v2
	v_bfe_u32 v3, v54, 16, 1
	v_add3_u32 v3, v54, v3, s74
	v_bfe_u32 v4, v55, 16, 1
	v_lshrrev_b32_e32 v3, 16, v3
	v_add3_u32 v4, v55, v4, s74
	v_and_or_b32 v3, v4, s73, v3
	s_waitcnt vmcnt(0)
	v_bfe_u32 v4, v64, 16, 1
	v_bfe_u32 v5, v65, 16, 1
	v_bfe_u32 v6, v66, 16, 1
	v_bfe_u32 v7, v67, 16, 1
	v_bfe_u32 v8, v60, 16, 1
	v_bfe_u32 v9, v61, 16, 1
	v_bfe_u32 v10, v62, 16, 1
	v_bfe_u32 v11, v63, 16, 1
	v_add_u32_e32 v12, v81, v175
	v_add3_u32 v4, v64, v4, s74
	v_add3_u32 v5, v65, v5, s74
	v_add3_u32 v6, v66, v6, s74
	v_add3_u32 v7, v67, v7, s74
	v_add3_u32 v8, v60, v8, s74
	v_add3_u32 v9, v61, v9, s74
	v_add3_u32 v10, v62, v10, s74
	v_add3_u32 v11, v63, v11, s74
	ds_write_b128 v12, v[0:3]
	ds_write_b16_d16_hi v176, v4
	ds_write_b16_d16_hi v176, v5 offset:528
	ds_write_b16_d16_hi v176, v6 offset:1056
	ds_write_b16_d16_hi v176, v7 offset:1584
	ds_write_b16_d16_hi v176, v8 offset:2112
	ds_write_b16_d16_hi v176, v9 offset:2640
	ds_write_b16_d16_hi v176, v10 offset:3168
	ds_write_b16_d16_hi v176, v11 offset:3696
	s_andn2_b64 vcc, exec, s[90:91]
	s_waitcnt lgkmcnt(0)
	s_barrier
	s_cbranch_vccnz .LBB0_692
	v_and_b32_e32 v0, -4, v38
	v_or_b32_e32 v1, 0x4000, v77
	v_add_u32_e32 v78, v0, v1
	v_mov_b64_e32 v[0:1], s[38:39]
	v_mad_u64_u32 v[0:1], s[0:1], v78, s97, v[0:1]
	s_lshl_b32 s80, s33, 8
	v_lshl_add_u64 v[0:1], v[0:1], 0, s[80:81]
	v_lshl_add_u64 v[0:1], v[88:89], 1, v[0:1]
	global_load_dwordx4 v[72:75], v[0:1], off offset:2560
	global_load_dwordx4 v[68:71], v[0:1], off offset:2624
	global_load_dwordx4 v[64:67], v[0:1], off offset:2688
	global_load_dwordx4 v[20:23], v[0:1], off offset:2752
	v_add_u32_e32 v24, v93, v95
	ds_read_b128 v[0:3], v24
	ds_read_b128 v[4:7], v24 offset:64
	v_add_u32_e32 v25, v93, v97
	v_readlane_b32 s4, v255, 49
	v_readlane_b32 s5, v255, 50
	s_waitcnt vmcnt(3) lgkmcnt(1)
	v_mfma_f32_16x16x32_bf16 v[0:3], v[0:3], v[72:75], 0
	ds_read_b128 v[26:29], v24 offset:17472
	ds_read_b128 v[30:33], v24 offset:21824
	ds_read_b128 v[12:15], v25 offset:64
	s_waitcnt vmcnt(2) lgkmcnt(3)
	v_mfma_f32_16x16x32_bf16 v[0:3], v[4:7], v[68:71], v[0:3]
	ds_read_b128 v[4:7], v24 offset:128
	ds_read_b128 v[82:85], v24 offset:56640
	ds_read_b128 v[130:133], v24 offset:60992
	s_waitcnt vmcnt(1) lgkmcnt(2)
	v_mfma_f32_16x16x32_bf16 v[0:3], v[4:7], v[64:67], v[0:3]
	ds_read_b128 v[4:7], v24 offset:192
	s_waitcnt vmcnt(0) lgkmcnt(0)
	v_mfma_f32_16x16x32_bf16 v[16:19], v[4:7], v[20:23], v[0:3]
	s_nop 4
	ds_read_b128 v[0:3], v24 offset:4352
	ds_read_b128 v[4:7], v24 offset:4416
	s_waitcnt lgkmcnt(1)
	v_mfma_f32_16x16x32_bf16 v[0:3], v[0:3], v[72:75], 0
	s_waitcnt lgkmcnt(0)
	v_mfma_f32_16x16x32_bf16 v[0:3], v[4:7], v[68:71], v[0:3]
	ds_read_b128 v[4:7], v24 offset:4480
	s_waitcnt lgkmcnt(0)
	v_mfma_f32_16x16x32_bf16 v[0:3], v[4:7], v[64:67], v[0:3]
	ds_read_b128 v[4:7], v24 offset:4544
	s_waitcnt lgkmcnt(0)
	v_mfma_f32_16x16x32_bf16 v[8:11], v[4:7], v[20:23], v[0:3]
	s_nop 4
	ds_read_b128 v[0:3], v24 offset:8704
	ds_read_b128 v[4:7], v24 offset:8768
	s_waitcnt lgkmcnt(1)
	v_mfma_f32_16x16x32_bf16 v[0:3], v[0:3], v[72:75], 0
	s_waitcnt lgkmcnt(0)
	v_mfma_f32_16x16x32_bf16 v[0:3], v[4:7], v[68:71], v[0:3]
	ds_read_b128 v[4:7], v24 offset:8832
	s_waitcnt lgkmcnt(0)
	v_mfma_f32_16x16x32_bf16 v[0:3], v[4:7], v[64:67], v[0:3]
	ds_read_b128 v[4:7], v24 offset:8896
	s_waitcnt lgkmcnt(0)
	v_mfma_f32_16x16x32_bf16 v[0:3], v[4:7], v[20:23], v[0:3]
	ds_read_b128 v[4:7], v25
	s_waitcnt lgkmcnt(0)
	v_mfma_f32_16x16x32_bf16 v[4:7], v[4:7], v[72:75], 0
	v_mfma_f32_16x16x32_bf16 v[4:7], v[12:15], v[68:71], v[4:7]
	ds_read_b128 v[12:15], v25 offset:128
	s_waitcnt lgkmcnt(0)
	v_mfma_f32_16x16x32_bf16 v[4:7], v[12:15], v[64:67], v[4:7]
	ds_read_b128 v[12:15], v25 offset:192
	v_add_u32_e32 v25, v93, v99
	ds_read_b128 v[36:39], v25 offset:64
	s_waitcnt lgkmcnt(1)
	v_mfma_f32_16x16x32_bf16 v[12:15], v[12:15], v[20:23], v[4:7]
	s_nop 2
	ds_read_b128 v[4:7], v24 offset:17408
	s_waitcnt lgkmcnt(0)
	v_mfma_f32_16x16x32_bf16 v[4:7], v[4:7], v[72:75], 0
	v_mfma_f32_16x16x32_bf16 v[4:7], v[26:29], v[68:71], v[4:7]
	ds_read_b128 v[26:29], v24 offset:17536
	s_waitcnt lgkmcnt(0)
	v_mfma_f32_16x16x32_bf16 v[4:7], v[26:29], v[64:67], v[4:7]
	ds_read_b128 v[26:29], v24 offset:17600
	s_waitcnt lgkmcnt(0)
	v_mfma_f32_16x16x32_bf16 v[4:7], v[26:29], v[20:23], v[4:7]
	ds_read_b128 v[26:29], v24 offset:21760
	s_waitcnt lgkmcnt(0)
	v_mfma_f32_16x16x32_bf16 v[26:29], v[26:29], v[72:75], 0
	v_mfma_f32_16x16x32_bf16 v[26:29], v[30:33], v[68:71], v[26:29]
	ds_read_b128 v[30:33], v24 offset:21888
	s_waitcnt lgkmcnt(0)
	v_mfma_f32_16x16x32_bf16 v[26:29], v[30:33], v[64:67], v[26:29]
	ds_read_b128 v[30:33], v24 offset:21952
	s_waitcnt lgkmcnt(0)
	v_mfma_f32_16x16x32_bf16 v[48:51], v[30:33], v[20:23], v[26:29]
	s_nop 4
	ds_read_b128 v[26:29], v24 offset:26112
	ds_read_b128 v[30:33], v24 offset:26176
	s_waitcnt lgkmcnt(1)
	v_mfma_f32_16x16x32_bf16 v[26:29], v[26:29], v[72:75], 0
	s_waitcnt lgkmcnt(0)
	v_mfma_f32_16x16x32_bf16 v[26:29], v[30:33], v[68:71], v[26:29]
	ds_read_b128 v[30:33], v24 offset:26240
	s_waitcnt lgkmcnt(0)
	v_mfma_f32_16x16x32_bf16 v[26:29], v[30:33], v[64:67], v[26:29]
	ds_read_b128 v[30:33], v24 offset:26304
	s_waitcnt lgkmcnt(0)
	v_mfma_f32_16x16x32_bf16 v[32:35], v[30:33], v[20:23], v[26:29]
	s_nop 4
	ds_read_b128 v[26:29], v25
	s_waitcnt lgkmcnt(0)
	v_mfma_f32_16x16x32_bf16 v[26:29], v[26:29], v[72:75], 0
	v_mfma_f32_16x16x32_bf16 v[26:29], v[36:39], v[68:71], v[26:29]
	ds_read_b128 v[36:39], v25 offset:128
	s_waitcnt lgkmcnt(0)
	v_mfma_f32_16x16x32_bf16 v[26:29], v[36:39], v[64:67], v[26:29]
	ds_read_b128 v[36:39], v25 offset:192
	v_add_u32_e32 v25, v93, v101
	s_waitcnt lgkmcnt(0)
	v_mfma_f32_16x16x32_bf16 v[60:63], v[36:39], v[20:23], v[26:29]
	s_nop 3
	ds_read_b128 v[26:29], v24 offset:34816
	ds_read_b128 v[36:39], v24 offset:34880
	s_waitcnt lgkmcnt(1)
	v_mfma_f32_16x16x32_bf16 v[26:29], v[26:29], v[72:75], 0
	s_waitcnt lgkmcnt(0)
	v_mfma_f32_16x16x32_bf16 v[26:29], v[36:39], v[68:71], v[26:29]
	ds_read_b128 v[36:39], v24 offset:34944
	s_waitcnt lgkmcnt(0)
	v_mfma_f32_16x16x32_bf16 v[26:29], v[36:39], v[64:67], v[26:29]
	ds_read_b128 v[36:39], v24 offset:35008
	s_waitcnt lgkmcnt(0)
	v_mfma_f32_16x16x32_bf16 v[56:59], v[36:39], v[20:23], v[26:29]
	s_nop 4
	ds_read_b128 v[26:29], v24 offset:39168
	ds_read_b128 v[36:39], v24 offset:39232
	s_waitcnt lgkmcnt(1)
	v_mfma_f32_16x16x32_bf16 v[26:29], v[26:29], v[72:75], 0
	s_waitcnt lgkmcnt(0)
	v_mfma_f32_16x16x32_bf16 v[26:29], v[36:39], v[68:71], v[26:29]
	ds_read_b128 v[36:39], v24 offset:39296
	s_waitcnt lgkmcnt(0)
	v_mfma_f32_16x16x32_bf16 v[26:29], v[36:39], v[64:67], v[26:29]
	ds_read_b128 v[36:39], v24 offset:39360
	s_waitcnt lgkmcnt(0)
	v_mfma_f32_16x16x32_bf16 v[52:55], v[36:39], v[20:23], v[26:29]
	s_nop 4
	ds_read_b128 v[26:29], v24 offset:43520
	ds_read_b128 v[36:39], v24 offset:43584
	s_waitcnt lgkmcnt(1)
	v_mfma_f32_16x16x32_bf16 v[26:29], v[26:29], v[72:75], 0
	s_waitcnt lgkmcnt(0)
	v_mfma_f32_16x16x32_bf16 v[26:29], v[36:39], v[68:71], v[26:29]
	ds_read_b128 v[36:39], v24 offset:43648
	s_waitcnt lgkmcnt(0)
	v_mfma_f32_16x16x32_bf16 v[26:29], v[36:39], v[64:67], v[26:29]
	ds_read_b128 v[36:39], v24 offset:43712
	s_waitcnt lgkmcnt(0)
	v_mfma_f32_16x16x32_bf16 v[44:47], v[36:39], v[20:23], v[26:29]
	s_nop 4
	ds_read_b128 v[26:29], v25
	ds_read_b128 v[36:39], v25 offset:64
	s_waitcnt lgkmcnt(1)
	v_mfma_f32_16x16x32_bf16 v[26:29], v[26:29], v[72:75], 0
	s_waitcnt lgkmcnt(0)
	v_mfma_f32_16x16x32_bf16 v[26:29], v[36:39], v[68:71], v[26:29]
	ds_read_b128 v[36:39], v25 offset:128
	s_waitcnt lgkmcnt(0)
	v_mfma_f32_16x16x32_bf16 v[26:29], v[36:39], v[64:67], v[26:29]
	ds_read_b128 v[36:39], v25 offset:192
	s_waitcnt lgkmcnt(0)
	v_mfma_f32_16x16x32_bf16 v[40:43], v[36:39], v[20:23], v[26:29]
	s_nop 4
	ds_read_b128 v[26:29], v24 offset:52224
	ds_read_b128 v[36:39], v24 offset:52288
	s_waitcnt lgkmcnt(1)
	v_mfma_f32_16x16x32_bf16 v[26:29], v[26:29], v[72:75], 0
	s_waitcnt lgkmcnt(0)
	v_mfma_f32_16x16x32_bf16 v[26:29], v[36:39], v[68:71], v[26:29]
	ds_read_b128 v[36:39], v24 offset:52352
	s_waitcnt lgkmcnt(0)
	v_mfma_f32_16x16x32_bf16 v[26:29], v[36:39], v[64:67], v[26:29]
	ds_read_b128 v[36:39], v24 offset:52416
	s_waitcnt lgkmcnt(0)
	v_mfma_f32_16x16x32_bf16 v[36:39], v[36:39], v[20:23], v[26:29]
	s_nop 4
	ds_read_b128 v[26:29], v24 offset:56576
	s_waitcnt lgkmcnt(0)
	v_mfma_f32_16x16x32_bf16 v[26:29], v[26:29], v[72:75], 0
	v_mfma_f32_16x16x32_bf16 v[26:29], v[82:85], v[68:71], v[26:29]
	ds_read_b128 v[82:85], v24 offset:56704
	s_waitcnt lgkmcnt(0)
	v_mfma_f32_16x16x32_bf16 v[26:29], v[82:85], v[64:67], v[26:29]
	ds_read_b128 v[82:85], v24 offset:56768
	s_waitcnt lgkmcnt(0)
	v_mfma_f32_16x16x32_bf16 v[28:31], v[82:85], v[20:23], v[26:29]
	ds_read_b128 v[82:85], v24 offset:60928
	s_waitcnt lgkmcnt(0)
	v_mfma_f32_16x16x32_bf16 v[82:85], v[82:85], v[72:75], 0
	v_mfma_f32_16x16x32_bf16 v[82:85], v[130:133], v[68:71], v[82:85]
	ds_read_b128 v[130:133], v24 offset:61056
	ds_read_b128 v[24:27], v24 offset:61120
	s_waitcnt lgkmcnt(1)
	v_mfma_f32_16x16x32_bf16 v[82:85], v[130:133], v[64:67], v[82:85]
	v_add_u32_e32 v130, v93, v103
	s_waitcnt lgkmcnt(0)
	v_mfma_f32_16x16x32_bf16 v[24:27], v[24:27], v[20:23], v[82:85]
	s_nop 4
	ds_read_b128 v[82:85], v130
	s_waitcnt lgkmcnt(0)
	v_mfma_f32_16x16x32_bf16 v[72:75], v[82:85], v[72:75], 0
	ds_read_b128 v[82:85], v130 offset:64
	s_waitcnt lgkmcnt(0)
	v_mfma_f32_16x16x32_bf16 v[68:71], v[82:85], v[68:71], v[72:75]
	s_nop 4
	ds_read_b128 v[72:75], v130 offset:128
	s_waitcnt lgkmcnt(0)
	v_mfma_f32_16x16x32_bf16 v[64:67], v[72:75], v[64:67], v[68:71]
	s_nop 2
	ds_read_b128 v[68:71], v130 offset:192
	s_waitcnt lgkmcnt(0)
	v_mfma_f32_16x16x32_bf16 v[20:23], v[68:71], v[20:23], v[64:67]
	s_nop 2
	v_mul_f32_e32 v64, 0x3db504f3, v16
	v_mul_f32_e32 v65, 0x3db504f3, v17
	v_max3_f32 v64, v64, s83, v65
	v_mul_f32_e32 v65, 0x3db504f3, v18
	v_mul_f32_e32 v66, 0x3db504f3, v19
	v_max3_f32 v64, v64, v65, v66
	v_mul_f32_e32 v65, 0x3db504f3, v8
	v_mul_f32_e32 v66, 0x3db504f3, v9
	v_max3_f32 v64, v64, v65, v66
	v_mul_f32_e32 v65, 0x3db504f3, v10
	v_mul_f32_e32 v66, 0x3db504f3, v11
	v_max3_f32 v64, v64, v65, v66
	v_mul_f32_e32 v65, 0x3db504f3, v0
	v_mul_f32_e32 v66, 0x3db504f3, v1
	v_max3_f32 v64, v64, v65, v66
	v_mul_f32_e32 v65, 0x3db504f3, v2
	v_mul_f32_e32 v66, 0x3db504f3, v3
	v_max3_f32 v64, v64, v65, v66
	v_mul_f32_e32 v65, 0x3db504f3, v12
	v_mul_f32_e32 v66, 0x3db504f3, v13
	v_max3_f32 v64, v64, v65, v66
	v_mul_f32_e32 v65, 0x3db504f3, v14
	v_mul_f32_e32 v66, 0x3db504f3, v15
	v_max3_f32 v64, v64, v65, v66
	v_mul_f32_e32 v65, 0x3db504f3, v4
	v_mul_f32_e32 v66, 0x3db504f3, v5
	v_max3_f32 v64, v64, v65, v66
	v_mul_f32_e32 v65, 0x3db504f3, v6
	v_mul_f32_e32 v66, 0x3db504f3, v7
	v_max3_f32 v64, v64, v65, v66
	v_mul_f32_e32 v65, 0x3db504f3, v48
	v_mul_f32_e32 v66, 0x3db504f3, v49
	v_max3_f32 v64, v64, v65, v66
	v_mul_f32_e32 v65, 0x3db504f3, v50
	v_mul_f32_e32 v66, 0x3db504f3, v51
	v_max3_f32 v64, v64, v65, v66
	v_mul_f32_e32 v65, 0x3db504f3, v32
	v_mul_f32_e32 v66, 0x3db504f3, v33
	v_max3_f32 v64, v64, v65, v66
	v_mul_f32_e32 v65, 0x3db504f3, v34
	v_mul_f32_e32 v66, 0x3db504f3, v35
	v_max3_f32 v64, v64, v65, v66
	v_mul_f32_e32 v65, 0x3db504f3, v60
	v_mul_f32_e32 v66, 0x3db504f3, v61
	v_max3_f32 v64, v64, v65, v66
	v_mul_f32_e32 v65, 0x3db504f3, v62
	v_mul_f32_e32 v66, 0x3db504f3, v63
	v_max3_f32 v64, v64, v65, v66
	v_mul_f32_e32 v65, 0x3db504f3, v56
	v_mul_f32_e32 v66, 0x3db504f3, v57
	v_max3_f32 v64, v64, v65, v66
	v_mul_f32_e32 v65, 0x3db504f3, v58
	v_mul_f32_e32 v66, 0x3db504f3, v59
	v_max3_f32 v64, v64, v65, v66
	v_mul_f32_e32 v65, 0x3db504f3, v52
	v_mul_f32_e32 v66, 0x3db504f3, v53
	v_max3_f32 v64, v64, v65, v66
	v_mul_f32_e32 v65, 0x3db504f3, v54
	v_mul_f32_e32 v66, 0x3db504f3, v55
	v_max3_f32 v64, v64, v65, v66
	v_mul_f32_e32 v65, 0x3db504f3, v44
	v_mul_f32_e32 v66, 0x3db504f3, v45
	v_max3_f32 v64, v64, v65, v66
	v_mul_f32_e32 v65, 0x3db504f3, v46
	v_mul_f32_e32 v66, 0x3db504f3, v47
	v_max3_f32 v64, v64, v65, v66
	v_mul_f32_e32 v65, 0x3db504f3, v40
	v_mul_f32_e32 v66, 0x3db504f3, v41
	v_max3_f32 v64, v64, v65, v66
	v_mul_f32_e32 v65, 0x3db504f3, v42
	v_mul_f32_e32 v66, 0x3db504f3, v43
	v_max3_f32 v64, v64, v65, v66
	v_mul_f32_e32 v65, 0x3db504f3, v36
	v_mul_f32_e32 v66, 0x3db504f3, v37
	v_max3_f32 v64, v64, v65, v66
	v_mul_f32_e32 v65, 0x3db504f3, v38
	v_mul_f32_e32 v66, 0x3db504f3, v39
	v_max3_f32 v64, v64, v65, v66
	v_mul_f32_e32 v65, 0x3db504f3, v28
	v_mul_f32_e32 v66, 0x3db504f3, v29
	v_max3_f32 v64, v64, v65, v66
	v_mul_f32_e32 v65, 0x3db504f3, v30
	v_mul_f32_e32 v66, 0x3db504f3, v31
	v_max3_f32 v64, v64, v65, v66
	v_mul_f32_e32 v65, 0x3db504f3, v24
	v_mul_f32_e32 v66, 0x3db504f3, v25
	v_max3_f32 v64, v64, v65, v66
	v_mul_f32_e32 v65, 0x3db504f3, v26
	v_mul_f32_e32 v66, 0x3db504f3, v27
	v_max3_f32 v64, v64, v65, v66
	v_mul_f32_e32 v65, 0x3db504f3, v20
	v_mul_f32_e32 v66, 0x3db504f3, v21
	v_max3_f32 v64, v64, v65, v66
	v_mul_f32_e32 v65, 0x3db504f3, v22
	v_mul_f32_e32 v66, 0x3db504f3, v23
	v_max3_f32 v64, v64, v65, v66
	v_and_b32_e32 v66, 64, v201
	v_xor_b32_e32 v65, 16, v201
	v_add_u32_e32 v66, 64, v66
	v_cmp_lt_i32_e32 vcc, v65, v66
	s_nop 1
	v_cndmask_b32_e32 v65, v201, v65, vcc
	v_lshlrev_b32_e32 v211, 2, v65
	ds_bpermute_b32 v65, v211, v64
	s_waitcnt lgkmcnt(0)
	v_max_f32_e32 v65, v65, v65
	v_max_f32_e32 v64, v64, v65
	v_xor_b32_e32 v65, 32, v201
	v_cmp_lt_i32_e32 vcc, v65, v66
	s_nop 1
	v_cndmask_b32_e32 v65, v201, v65, vcc
	v_lshlrev_b32_e32 v212, 2, v65
	ds_bpermute_b32 v65, v212, v64
	s_waitcnt lgkmcnt(0)
	v_max_f32_e32 v65, v65, v65
	v_max_f32_e32 v213, v64, v65
	v_fma_f32 v1, v1, s82, -v213
	v_mul_f32_e32 v1, 0x3fb8aa3b, v1
	v_exp_f32_e32 v131, v1
	v_fma_f32 v1, v2, s82, -v213
	v_mul_f32_e32 v1, 0x3fb8aa3b, v1
	v_exp_f32_e32 v132, v1
	v_fma_f32 v1, v3, s82, -v213
	v_mul_f32_e32 v1, 0x3fb8aa3b, v1
	v_exp_f32_e32 v133, v1
	v_fma_f32 v1, v12, s82, -v213
	v_mul_f32_e32 v1, 0x3fb8aa3b, v1
	v_exp_f32_e32 v134, v1
	v_fma_f32 v1, v13, s82, -v213
	v_mul_f32_e32 v1, 0x3fb8aa3b, v1
	v_exp_f32_e32 v135, v1
	v_fma_f32 v1, v14, s82, -v213
	v_mul_f32_e32 v1, 0x3fb8aa3b, v1
	v_exp_f32_e32 v136, v1
	v_fma_f32 v1, v15, s82, -v213
	v_mul_f32_e32 v1, 0x3fb8aa3b, v1
	v_exp_f32_e32 v137, v1
	v_fma_f32 v1, v4, s82, -v213
	v_mul_f32_e32 v1, 0x3fb8aa3b, v1
	v_exp_f32_e32 v68, v1
	v_fma_f32 v1, v5, s82, -v213
	v_mul_f32_e32 v1, 0x3fb8aa3b, v1
	v_exp_f32_e32 v69, v1
	v_fma_f32 v1, v6, s82, -v213
	v_mul_f32_e32 v1, 0x3fb8aa3b, v1
	v_exp_f32_e32 v70, v1
	v_fma_f32 v1, v7, s82, -v213
	v_mul_f32_e32 v1, 0x3fb8aa3b, v1
	v_exp_f32_e32 v71, v1
	v_fma_f32 v1, v48, s82, -v213
	v_mul_f32_e32 v1, 0x3fb8aa3b, v1
	v_exp_f32_e32 v72, v1
	v_fma_f32 v1, v49, s82, -v213
	v_mul_f32_e32 v1, 0x3fb8aa3b, v1
	v_exp_f32_e32 v73, v1
	v_fma_f32 v1, v50, s82, -v213
	v_mul_f32_e32 v1, 0x3fb8aa3b, v1
	v_exp_f32_e32 v74, v1
	v_fma_f32 v1, v51, s82, -v213
	v_mul_f32_e32 v1, 0x3fb8aa3b, v1
	v_exp_f32_e32 v75, v1
	v_fma_f32 v1, v32, s82, -v213
	v_mul_f32_e32 v1, 0x3fb8aa3b, v1
	v_exp_f32_e32 v64, v1
	v_fma_f32 v1, v33, s82, -v213
	v_mul_f32_e32 v1, 0x3fb8aa3b, v1
	v_exp_f32_e32 v65, v1
	v_fma_f32 v1, v34, s82, -v213
	v_mul_f32_e32 v1, 0x3fb8aa3b, v1
	v_fma_f32 v17, v17, s82, -v213
	v_exp_f32_e32 v66, v1
	v_fma_f32 v1, v35, s82, -v213
	v_fma_f32 v16, v16, s82, -v213
	v_mul_f32_e32 v17, 0x3fb8aa3b, v17
	v_mul_f32_e32 v1, 0x3fb8aa3b, v1
	v_mul_f32_e32 v16, 0x3fb8aa3b, v16
	v_exp_f32_e32 v139, v17
	v_fma_f32 v17, v18, s82, -v213
	v_exp_f32_e32 v67, v1
	v_fma_f32 v1, v60, s82, -v213
	v_exp_f32_e32 v138, v16
	v_mul_f32_e32 v17, 0x3fb8aa3b, v17
	v_mul_f32_e32 v1, 0x3fb8aa3b, v1
	v_exp_f32_e32 v140, v17
	v_fma_f32 v17, v19, s82, -v213
	v_fma_f32 v9, v9, s82, -v213
	v_exp_f32_e32 v60, v1
	v_fma_f32 v1, v61, s82, -v213
	v_mul_f32_e32 v17, 0x3fb8aa3b, v17
	v_fma_f32 v8, v8, s82, -v213
	v_mul_f32_e32 v9, 0x3fb8aa3b, v9
	v_mul_f32_e32 v1, 0x3fb8aa3b, v1
	v_exp_f32_e32 v141, v17
	v_mul_f32_e32 v8, 0x3fb8aa3b, v8
	v_exp_f32_e32 v143, v9
	v_fma_f32 v9, v10, s82, -v213
	v_exp_f32_e32 v61, v1
	v_fma_f32 v1, v62, s82, -v213
	v_add_f32_e32 v16, 0, v138
	v_exp_f32_e32 v142, v8
	v_mul_f32_e32 v9, 0x3fb8aa3b, v9
	v_mul_f32_e32 v1, 0x3fb8aa3b, v1
	v_add_f32_e32 v16, v139, v16
	v_exp_f32_e32 v144, v9
	v_fma_f32 v9, v11, s82, -v213
	v_exp_f32_e32 v62, v1
	v_fma_f32 v1, v63, s82, -v213
	v_add_f32_e32 v16, v140, v16
	v_mul_f32_e32 v9, 0x3fb8aa3b, v9
	v_fma_f32 v0, v0, s82, -v213
	v_mul_f32_e32 v1, 0x3fb8aa3b, v1
	v_add_f32_e32 v16, v141, v16
	v_exp_f32_e32 v145, v9
	v_mul_f32_e32 v0, 0x3fb8aa3b, v0
	v_exp_f32_e32 v63, v1
	v_fma_f32 v1, v56, s82, -v213
	v_add_f32_e32 v8, v142, v16
	v_exp_f32_e32 v130, v0
	v_mul_f32_e32 v1, 0x3fb8aa3b, v1
	v_add_f32_e32 v8, v143, v8
	v_exp_f32_e32 v48, v1
	v_fma_f32 v1, v57, s82, -v213
	v_add_f32_e32 v8, v144, v8
	v_mul_f32_e32 v1, 0x3fb8aa3b, v1
	v_add_f32_e32 v8, v145, v8
	v_exp_f32_e32 v49, v1
	v_fma_f32 v1, v58, s82, -v213
	v_add_f32_e32 v0, v130, v8
	v_mul_f32_e32 v1, 0x3fb8aa3b, v1
	v_add_f32_e32 v0, v131, v0
	v_exp_f32_e32 v50, v1
	v_fma_f32 v1, v59, s82, -v213
	v_add_f32_e32 v0, v132, v0
	v_mul_f32_e32 v1, 0x3fb8aa3b, v1
	v_add_f32_e32 v0, v133, v0
	v_exp_f32_e32 v51, v1
	v_fma_f32 v1, v52, s82, -v213
	v_add_f32_e32 v0, v134, v0
	v_mul_f32_e32 v1, 0x3fb8aa3b, v1
	v_add_f32_e32 v0, v135, v0
	v_exp_f32_e32 v52, v1
	v_fma_f32 v1, v53, s82, -v213
	v_add_f32_e32 v0, v136, v0
	v_mul_f32_e32 v1, 0x3fb8aa3b, v1
	v_add_f32_e32 v0, v137, v0
	v_exp_f32_e32 v53, v1
	v_fma_f32 v1, v54, s82, -v213
	v_add_f32_e32 v0, v68, v0
	v_mul_f32_e32 v1, 0x3fb8aa3b, v1
	v_add_f32_e32 v0, v69, v0
	v_exp_f32_e32 v54, v1
	v_fma_f32 v1, v55, s82, -v213
	v_add_f32_e32 v0, v70, v0
	v_mul_f32_e32 v1, 0x3fb8aa3b, v1
	v_add_f32_e32 v0, v71, v0
	v_exp_f32_e32 v55, v1
	v_fma_f32 v1, v44, s82, -v213
	v_add_f32_e32 v0, v72, v0
	v_mul_f32_e32 v1, 0x3fb8aa3b, v1
	v_add_f32_e32 v0, v73, v0
	v_exp_f32_e32 v18, v1
	v_fma_f32 v1, v45, s82, -v213
	v_add_f32_e32 v0, v74, v0
	v_mul_f32_e32 v1, 0x3fb8aa3b, v1
	v_add_f32_e32 v0, v75, v0
	v_exp_f32_e32 v19, v1
	v_fma_f32 v1, v46, s82, -v213
	v_add_f32_e32 v0, v64, v0
	v_mul_f32_e32 v1, 0x3fb8aa3b, v1
	v_add_f32_e32 v0, v65, v0
	v_exp_f32_e32 v32, v1
	v_fma_f32 v1, v47, s82, -v213
	v_add_f32_e32 v0, v66, v0
	v_mul_f32_e32 v1, 0x3fb8aa3b, v1
	v_add_f32_e32 v0, v67, v0
	v_exp_f32_e32 v33, v1
	v_fma_f32 v1, v40, s82, -v213
	v_add_f32_e32 v0, v60, v0
	v_mul_f32_e32 v1, 0x3fb8aa3b, v1
	v_add_f32_e32 v0, v61, v0
	v_exp_f32_e32 v34, v1
	v_fma_f32 v1, v41, s82, -v213
	v_add_f32_e32 v0, v62, v0
	v_mul_f32_e32 v1, 0x3fb8aa3b, v1
	v_add_f32_e32 v0, v63, v0
	v_exp_f32_e32 v35, v1
	v_fma_f32 v1, v42, s82, -v213
	v_add_f32_e32 v0, v48, v0
	v_mul_f32_e32 v1, 0x3fb8aa3b, v1
	v_add_f32_e32 v0, v49, v0
	v_exp_f32_e32 v40, v1
	v_fma_f32 v1, v43, s82, -v213
	v_add_f32_e32 v0, v50, v0
	v_mul_f32_e32 v1, 0x3fb8aa3b, v1
	v_add_f32_e32 v0, v51, v0
	v_exp_f32_e32 v41, v1
	v_fma_f32 v1, v36, s82, -v213
	v_add_f32_e32 v0, v52, v0
	v_mul_f32_e32 v1, 0x3fb8aa3b, v1
	v_add_f32_e32 v0, v53, v0
	v_exp_f32_e32 v10, v1
	v_fma_f32 v1, v37, s82, -v213
	v_add_f32_e32 v0, v54, v0
	v_mul_f32_e32 v1, 0x3fb8aa3b, v1
	v_add_f32_e32 v0, v55, v0
	v_exp_f32_e32 v11, v1
	v_fma_f32 v1, v38, s82, -v213
	v_add_f32_e32 v0, v18, v0
	v_mul_f32_e32 v1, 0x3fb8aa3b, v1
	v_add_f32_e32 v0, v19, v0
	v_exp_f32_e32 v12, v1
	v_fma_f32 v1, v39, s82, -v213
	v_add_f32_e32 v0, v32, v0
	v_mul_f32_e32 v1, 0x3fb8aa3b, v1
	v_add_f32_e32 v0, v33, v0
	v_exp_f32_e32 v13, v1
	v_fma_f32 v1, v28, s82, -v213
	v_add_f32_e32 v0, v34, v0
	v_mul_f32_e32 v1, 0x3fb8aa3b, v1
	v_add_f32_e32 v0, v35, v0
	v_exp_f32_e32 v14, v1
	v_fma_f32 v1, v29, s82, -v213
	v_add_f32_e32 v0, v40, v0
	v_mul_f32_e32 v1, 0x3fb8aa3b, v1
	v_add_f32_e32 v0, v41, v0
	v_exp_f32_e32 v15, v1
	v_fma_f32 v1, v30, s82, -v213
	v_add_f32_e32 v0, v10, v0
	v_mul_f32_e32 v1, 0x3fb8aa3b, v1
	v_add_f32_e32 v0, v11, v0
	v_exp_f32_e32 v16, v1
	v_fma_f32 v1, v31, s82, -v213
	v_add_f32_e32 v0, v12, v0
	v_mul_f32_e32 v1, 0x3fb8aa3b, v1
	v_add_f32_e32 v0, v13, v0
	v_exp_f32_e32 v17, v1
	v_add_f32_e32 v0, v14, v0
	v_add_f32_e32 v0, v15, v0
	v_add_f32_e32 v0, v16, v0
	v_add_f32_e32 v1, v17, v0
	v_fma_f32 v0, v24, s82, -v213
	v_mul_f32_e32 v0, 0x3fb8aa3b, v0
	v_exp_f32_e32 v0, v0
	ds_read2_b64 v[28:31], v111 offset1:4
	v_add_f32_e32 v2, v0, v1
	v_fma_f32 v1, v25, s82, -v213
	v_mul_f32_e32 v1, 0x3fb8aa3b, v1
	v_exp_f32_e32 v1, v1
	s_nop 0
	v_add_f32_e32 v3, v1, v2
	v_fma_f32 v2, v26, s82, -v213
	v_mul_f32_e32 v2, 0x3fb8aa3b, v2
	v_exp_f32_e32 v2, v2
	s_nop 0
	v_add_f32_e32 v4, v2, v3
	v_fma_f32 v3, v27, s82, -v213
	v_mul_f32_e32 v3, 0x3fb8aa3b, v3
	v_exp_f32_e32 v3, v3
	s_nop 0
	v_add_f32_e32 v5, v3, v4
	v_fma_f32 v4, v20, s82, -v213
	v_mul_f32_e32 v4, 0x3fb8aa3b, v4
	v_exp_f32_e32 v4, v4
	s_nop 0
	v_add_f32_e32 v6, v4, v5
	v_fma_f32 v5, v21, s82, -v213
	v_mul_f32_e32 v5, 0x3fb8aa3b, v5
	v_exp_f32_e32 v5, v5
	s_nop 0
	v_add_f32_e32 v7, v5, v6
	v_fma_f32 v6, v22, s82, -v213
	v_mul_f32_e32 v6, 0x3fb8aa3b, v6
	v_exp_f32_e32 v6, v6
	s_nop 0
	v_add_f32_e32 v8, v6, v7
	v_fma_f32 v7, v23, s82, -v213
	v_mul_f32_e32 v7, 0x3fb8aa3b, v7
	v_exp_f32_e32 v7, v7
	s_nop 0
	v_add_f32_e32 v8, v7, v8
	ds_bpermute_b32 v9, v211, v8
	s_waitcnt lgkmcnt(0)
	v_add_f32_e32 v8, v8, v9
	ds_bpermute_b32 v9, v212, v8
	s_waitcnt lgkmcnt(0)
	v_add_f32_e32 v8, v8, v9
	v_div_scale_f32 v9, s[0:1], v8, v8, 1.0
	v_rcp_f32_e32 v20, v9
	s_nop 0
	v_fma_f32 v21, -v9, v20, 1.0
	v_fmac_f32_e32 v20, v21, v20
	v_div_scale_f32 v21, vcc, 1.0, v8, 1.0
	v_mul_f32_e32 v22, v21, v20
	v_fma_f32 v23, -v9, v22, v21
	v_fmac_f32_e32 v22, v23, v20
	v_fma_f32 v9, -v9, v22, v21
	v_div_fmas_f32 v9, v9, v20, v22
	v_div_fixup_f32 v8, v9, v8, 1.0
	v_pk_mul_f32 v[20:21], v[138:139], v[8:9] op_sel_hi:[1,0]
	v_pk_mul_f32 v[22:23], v[140:141], v[8:9] op_sel_hi:[1,0]
	v_cvt_pk_bf16_f32 v20, v20, v21
	v_cvt_pk_bf16_f32 v21, v22, v23
	v_pk_mul_f32 v[22:23], v[142:143], v[8:9] op_sel_hi:[1,0]
	v_pk_mul_f32 v[24:25], v[144:145], v[8:9] op_sel_hi:[1,0]
	v_cvt_pk_bf16_f32 v22, v22, v23
	v_cvt_pk_bf16_f32 v23, v24, v25
	ds_read2_b64 v[24:27], v107 offset1:4
	ds_read2_b64 v[36:39], v113 offset1:8
	ds_read2_b64 v[42:45], v146 offset1:8
	ds_read2_b64 v[82:85], v148 offset1:8
	ds_read2_b64 v[138:141], v149 offset1:8
	ds_read2_b64 v[212:215], v150 offset0:8 offset1:12
	ds_read2_b64 v[216:219], v151 offset0:8 offset1:12
	ds_read2_b64 v[220:223], v152 offset1:8
	ds_read2_b64 v[224:227], v153 offset1:8
	s_waitcnt lgkmcnt(7)
	v_mov_b32_e32 v56, v36
	v_mov_b32_e32 v57, v37
	v_pk_mul_f32 v[36:37], v[130:131], v[8:9] op_sel_hi:[1,0]
	s_waitcnt lgkmcnt(1)
	v_mov_b32_e32 v228, v222
	v_mov_b32_e32 v229, v223
	s_waitcnt lgkmcnt(0)
	v_mov_b32_e32 v230, v226
	v_mov_b32_e32 v231, v227
	v_cvt_pk_bf16_f32 v130, v36, v37
	v_pk_mul_f32 v[36:37], v[132:133], v[8:9] op_sel_hi:[1,0]
	v_mfma_f32_16x16x32_bf16 v[226:229], v[228:231], v[20:23], 0
	v_cvt_pk_bf16_f32 v131, v36, v37
	v_pk_mul_f32 v[36:37], v[134:135], v[8:9] op_sel_hi:[1,0]
	ds_read2_b64 v[230:233], v154 offset1:8
	ds_read2_b64 v[234:237], v155 offset1:8
	v_cvt_pk_bf16_f32 v132, v36, v37
	v_pk_mul_f32 v[36:37], v[136:137], v[8:9] op_sel_hi:[1,0]
	ds_read2_b64 v[134:137], v107 offset0:8 offset1:12
	v_pk_mul_f32 v[46:47], v[68:69], v[8:9] op_sel_hi:[1,0]
	v_mov_b32_e32 v58, v42
	v_cvt_pk_bf16_f32 v68, v46, v47
	v_pk_mul_f32 v[46:47], v[70:71], v[8:9] op_sel_hi:[1,0]
	v_mov_b32_e32 v59, v43
	v_cvt_pk_bf16_f32 v69, v46, v47
	v_pk_mul_f32 v[46:47], v[72:73], v[8:9] op_sel_hi:[1,0]
	v_mfma_f32_16x16x32_bf16 v[24:27], v[24:27], v[20:23], 0
	v_cvt_pk_bf16_f32 v70, v46, v47
	v_pk_mul_f32 v[46:47], v[74:75], v[8:9] op_sel_hi:[1,0]
	ds_read2_b64 v[72:75], v107 offset0:16 offset1:20
	v_cvt_pk_bf16_f32 v133, v36, v37
	v_mov_b32_e32 v42, v38
	v_mov_b32_e32 v43, v39
	v_mfma_f32_16x16x32_bf16 v[56:59], v[56:59], v[20:23], 0
	v_cvt_pk_bf16_f32 v71, v46, v47
	v_mov_b32_e32 v142, v82
	v_mov_b32_e32 v143, v83
	s_waitcnt lgkmcnt(1)
	v_mfma_f32_16x16x32_bf16 v[24:27], v[134:137], v[130:133], v[24:27]
	ds_read2_b64 v[134:137], v111 offset0:8 offset1:12
	v_mov_b32_e32 v144, v138
	v_mov_b32_e32 v145, v139
	v_mov_b32_e32 v238, v232
	v_mov_b32_e32 v239, v233
	v_mov_b32_e32 v240, v236
	v_mov_b32_e32 v241, v237
	v_mfma_f32_16x16x32_bf16 v[36:39], v[42:45], v[130:133], v[56:59]
	v_mov_b32_e32 v138, v84
	v_mov_b32_e32 v139, v85
	ds_read2_b64 v[82:85], v151 offset1:4
	ds_read2_b64 v[56:59], v150 offset1:4
	s_waitcnt lgkmcnt(3)
	v_mfma_f32_16x16x32_bf16 v[24:27], v[72:75], v[68:71], v[24:27]
	ds_read2_b64 v[72:75], v111 offset0:16 offset1:20
	v_mov_b32_e32 v222, v224
	v_mov_b32_e32 v223, v225
	v_mfma_f32_16x16x32_bf16 v[28:31], v[28:31], v[20:23], 0
	v_mov_b32_e32 v232, v234
	v_mov_b32_e32 v233, v235
	v_pk_mul_f32 v[46:47], v[64:65], v[8:9] op_sel_hi:[1,0]
	v_mfma_f32_16x16x32_bf16 v[142:145], v[142:145], v[20:23], 0
	v_cvt_pk_bf16_f32 v64, v46, v47
	v_pk_mul_f32 v[46:47], v[66:67], v[8:9] op_sel_hi:[1,0]
	v_pk_mul_f32 v[18:19], v[18:19], v[8:9] op_sel_hi:[1,0]
	v_mfma_f32_16x16x32_bf16 v[212:215], v[212:215], v[20:23], 0
	v_cvt_pk_bf16_f32 v65, v46, v47
	v_pk_mul_f32 v[46:47], v[60:61], v[8:9] op_sel_hi:[1,0]
	v_pk_mul_f32 v[10:11], v[10:11], v[8:9] op_sel_hi:[1,0]
	v_mfma_f32_16x16x32_bf16 v[216:219], v[216:219], v[20:23], 0
	v_cvt_pk_bf16_f32 v66, v46, v47
	v_pk_mul_f32 v[46:47], v[62:63], v[8:9] op_sel_hi:[1,0]
	v_pk_mul_f32 v[12:13], v[12:13], v[8:9] op_sel_hi:[1,0]
	v_mfma_f32_16x16x32_bf16 v[20:23], v[238:241], v[20:23], 0
	v_cvt_pk_bf16_f32 v67, v46, v47
	v_pk_mul_f32 v[46:47], v[48:49], v[8:9] op_sel_hi:[1,0]
	v_pk_mul_f32 v[48:49], v[50:51], v[8:9] op_sel_hi:[1,0]
	s_waitcnt lgkmcnt(3)
	v_mfma_f32_16x16x32_bf16 v[28:31], v[134:137], v[130:133], v[28:31]
	v_cvt_pk_bf16_f32 v46, v46, v47
	v_cvt_pk_bf16_f32 v47, v48, v49
	v_pk_mul_f32 v[48:49], v[52:53], v[8:9] op_sel_hi:[1,0]
	v_mfma_f32_16x16x32_bf16 v[42:45], v[138:141], v[130:133], v[142:145]
	v_mul_f32_e64 v50, v54, v8
	v_mul_f32_e64 v51, v55, v8
	v_cvt_pk_bf16_f32 v48, v48, v49
	v_cvt_pk_bf16_f32 v49, v50, v51
	s_waitcnt lgkmcnt(1)
	v_mfma_f32_16x16x32_bf16 v[56:59], v[56:59], v[130:133], v[212:215]
	v_cvt_pk_bf16_f32 v10, v10, v11
	v_cvt_pk_bf16_f32 v11, v12, v13
	v_pk_mul_f32 v[12:13], v[14:15], v[8:9] op_sel_hi:[1,0]
	v_mfma_f32_16x16x32_bf16 v[82:85], v[82:85], v[130:133], v[216:219]
	v_mul_f32_e64 v14, v16, v8
	v_mul_f32_e64 v15, v17, v8
	v_cvt_pk_bf16_f32 v12, v12, v13
	v_cvt_pk_bf16_f32 v13, v14, v15
	v_mfma_f32_16x16x32_bf16 v[134:137], v[220:223], v[130:133], v[226:229]
	v_mul_f32_e64 v0, v0, v8
	v_mul_f32_e64 v1, v1, v8
	v_pk_mul_f32 v[2:3], v[2:3], v[8:9] op_sel_hi:[1,0]
	v_cvt_pk_bf16_f32 v0, v0, v1
	v_mfma_f32_16x16x32_bf16 v[20:23], v[230:233], v[130:133], v[20:23]
	v_cvt_pk_bf16_f32 v1, v2, v3
	v_pk_mul_f32 v[2:3], v[4:5], v[8:9] op_sel_hi:[1,0]
	v_pk_mul_f32 v[4:5], v[6:7], v[8:9] op_sel_hi:[1,0]
	s_waitcnt lgkmcnt(0)
	v_mfma_f32_16x16x32_bf16 v[28:31], v[72:75], v[68:71], v[28:31]
	ds_read2_b64 v[72:75], v113 offset0:16 offset1:24
	ds_read2_b64 v[130:133], v146 offset0:16 offset1:24
	v_cvt_pk_bf16_f32 v2, v2, v3
	v_cvt_pk_bf16_f32 v3, v4, v5
	s_waitcnt lgkmcnt(1)
	v_mov_b32_e32 v138, v72
	v_mov_b32_e32 v139, v73
	s_waitcnt lgkmcnt(0)
	v_mov_b32_e32 v140, v130
	v_mov_b32_e32 v141, v131
	v_mov_b32_e32 v130, v74
	v_mov_b32_e32 v131, v75
	v_mfma_f32_16x16x32_bf16 v[36:39], v[138:141], v[68:71], v[36:39]
	ds_read2_b64 v[138:141], v148 offset0:16 offset1:24
	ds_read2_b64 v[142:145], v149 offset0:16 offset1:24
	s_waitcnt lgkmcnt(1)
	v_mov_b32_e32 v212, v138
	v_mov_b32_e32 v213, v139
	s_waitcnt lgkmcnt(0)
	v_mov_b32_e32 v214, v142
	v_mov_b32_e32 v215, v143
	v_mov_b32_e32 v142, v140
	v_mov_b32_e32 v143, v141
	v_mfma_f32_16x16x32_bf16 v[42:45], v[212:215], v[68:71], v[42:45]
	ds_read2_b64 v[212:215], v150 offset0:24 offset1:28
	s_waitcnt lgkmcnt(0)
	v_mfma_f32_16x16x32_bf16 v[56:59], v[212:215], v[68:71], v[56:59]
	ds_read2_b64 v[212:215], v151 offset0:24 offset1:28
	s_waitcnt lgkmcnt(0)
	v_mfma_f32_16x16x32_bf16 v[82:85], v[212:215], v[68:71], v[82:85]
	ds_read2_b64 v[212:215], v152 offset0:16 offset1:24
	ds_read2_b64 v[216:219], v153 offset0:16 offset1:24
	s_waitcnt lgkmcnt(1)
	v_mov_b32_e32 v220, v214
	v_mov_b32_e32 v221, v215
	s_waitcnt lgkmcnt(0)
	v_mov_b32_e32 v222, v218
	v_mov_b32_e32 v223, v219
	v_mov_b32_e32 v214, v216
	v_mov_b32_e32 v215, v217
	v_mfma_f32_16x16x32_bf16 v[134:137], v[220:223], v[68:71], v[134:137]
	ds_read2_b64 v[218:221], v154 offset0:16 offset1:24
	ds_read2_b64 v[222:225], v155 offset0:16 offset1:24
	ds_read2_b64 v[60:63], v107 offset0:24 offset1:28
	ds_read2_b64 v[50:53], v107 offset0:32 offset1:36
	s_waitcnt lgkmcnt(1)
	v_mfma_f32_16x16x32_bf16 v[24:27], v[60:63], v[64:67], v[24:27]
	ds_read2_b64 v[60:63], v111 offset0:24 offset1:28
	v_mov_b32_e32 v226, v220
	v_mov_b32_e32 v227, v221
	s_waitcnt lgkmcnt(0)
	v_mfma_f32_16x16x32_bf16 v[28:31], v[60:63], v[64:67], v[28:31]
	ds_read2_b64 v[60:63], v150 offset0:16 offset1:20
	v_mov_b32_e32 v228, v224
	v_mov_b32_e32 v229, v225
	s_waitcnt lgkmcnt(0)
	v_mfma_f32_16x16x32_bf16 v[56:59], v[60:63], v[64:67], v[56:59]
	ds_read2_b64 v[60:63], v151 offset0:16 offset1:20
	v_mov_b32_e32 v220, v222
	v_mov_b32_e32 v221, v223
	v_mfma_f32_16x16x32_bf16 v[24:27], v[50:53], v[46:49], v[24:27]
	ds_read2_b64 v[50:53], v111 offset0:32 offset1:36
	v_mfma_f32_16x16x32_bf16 v[20:23], v[226:229], v[68:71], v[20:23]
	v_mfma_f32_16x16x32_bf16 v[36:39], v[130:133], v[64:67], v[36:39]
	v_mfma_f32_16x16x32_bf16 v[42:45], v[142:145], v[64:67], v[42:45]
	s_waitcnt lgkmcnt(1)
	v_mfma_f32_16x16x32_bf16 v[60:63], v[60:63], v[64:67], v[82:85]
	v_mfma_f32_16x16x32_bf16 v[68:71], v[212:215], v[64:67], v[134:137]
	v_mfma_f32_16x16x32_bf16 v[20:23], v[218:221], v[64:67], v[20:23]
	s_waitcnt lgkmcnt(0)
	v_mfma_f32_16x16x32_bf16 v[28:31], v[50:53], v[46:49], v[28:31]
	ds_read2_b64 v[50:53], v113 offset0:32 offset1:40
	ds_read2_b64 v[64:67], v146 offset0:32 offset1:40
	s_waitcnt lgkmcnt(1)
	v_mov_b32_e32 v72, v50
	v_mov_b32_e32 v73, v51
	s_waitcnt lgkmcnt(0)
	v_mov_b32_e32 v74, v64
	v_mov_b32_e32 v75, v65
	s_nop 1
	v_mfma_f32_16x16x32_bf16 v[36:39], v[72:75], v[46:49], v[36:39]
	ds_read2_b64 v[72:75], v148 offset0:32 offset1:40
	ds_read2_b64 v[82:85], v149 offset0:32 offset1:40
	s_waitcnt lgkmcnt(1)
	v_mov_b32_e32 v130, v72
	v_mov_b32_e32 v131, v73
	s_waitcnt lgkmcnt(0)
	v_mov_b32_e32 v132, v82
	v_mov_b32_e32 v133, v83
	v_mov_b32_e32 v82, v74
	v_mov_b32_e32 v83, v75
	v_mfma_f32_16x16x32_bf16 v[42:45], v[130:133], v[46:49], v[42:45]
	ds_read2_b64 v[130:133], v150 offset0:40 offset1:44
	s_waitcnt lgkmcnt(0)
	v_mfma_f32_16x16x32_bf16 v[54:57], v[130:133], v[46:49], v[56:59]
	ds_read2_b64 v[130:133], v151 offset0:40 offset1:44
	s_waitcnt lgkmcnt(0)
	v_mfma_f32_16x16x32_bf16 v[58:61], v[130:133], v[46:49], v[60:63]
	s_nop 2
	ds_read2_b64 v[62:65], v152 offset0:32 offset1:40
	ds_read2_b64 v[130:133], v153 offset0:32 offset1:40
	s_waitcnt lgkmcnt(1)
	v_mov_b32_e32 v134, v64
	v_mov_b32_e32 v135, v65
	s_waitcnt lgkmcnt(0)
	v_mov_b32_e32 v136, v132
	v_mov_b32_e32 v137, v133
	v_mov_b32_e32 v64, v52
	v_mov_b32_e32 v65, v53
	v_mfma_f32_16x16x32_bf16 v[68:71], v[134:137], v[46:49], v[68:71]
	ds_read2_b64 v[132:135], v154 offset0:32 offset1:40
	ds_read2_b64 v[136:139], v155 offset0:32 offset1:40
	ds_read2_b64 v[14:17], v107 offset0:48 offset1:52
	ds_read2_b64 v[50:53], v151 offset0:32 offset1:36
	s_waitcnt lgkmcnt(3)
	v_mov_b32_e32 v140, v134
	v_mov_b32_e32 v141, v135
	s_waitcnt lgkmcnt(2)
	v_mov_b32_e32 v142, v138
	v_mov_b32_e32 v143, v139
	v_mov_b32_e32 v134, v136
	v_mov_b32_e32 v135, v137
	v_mfma_f32_16x16x32_bf16 v[20:23], v[140:143], v[46:49], v[20:23]
	v_cvt_pk_bf16_f32 v46, v18, v19
	v_pk_mul_f32 v[18:19], v[32:33], v[8:9] op_sel_hi:[1,0]
	s_nop 0
	v_cvt_pk_bf16_f32 v47, v18, v19
	v_pk_mul_f32 v[18:19], v[34:35], v[8:9] op_sel_hi:[1,0]
	ds_read2_b64 v[32:35], v107 offset0:40 offset1:44
	v_cvt_pk_bf16_f32 v48, v18, v19
	v_pk_mul_f32 v[18:19], v[40:41], v[8:9] op_sel_hi:[1,0]
	s_nop 0
	v_cvt_pk_bf16_f32 v49, v18, v19
	s_waitcnt lgkmcnt(0)
	s_nop 0
	v_mfma_f32_16x16x32_bf16 v[24:27], v[32:35], v[46:49], v[24:27]
	ds_read2_b64 v[32:35], v111 offset0:40 offset1:44
	s_waitcnt lgkmcnt(0)
	v_mfma_f32_16x16x32_bf16 v[28:31], v[32:35], v[46:49], v[28:31]
	v_mfma_f32_16x16x32_bf16 v[32:35], v[64:67], v[46:49], v[36:39]
	v_mov_b32_e32 v64, v130
	v_mov_b32_e32 v65, v131
	v_mfma_f32_16x16x32_bf16 v[36:39], v[82:85], v[46:49], v[42:45]
	s_nop 2
	ds_read2_b64 v[40:43], v150 offset0:32 offset1:36
	v_mfma_f32_16x16x32_bf16 v[18:21], v[132:135], v[46:49], v[20:23]
	v_mfma_f32_16x16x32_bf16 v[14:17], v[14:17], v[10:13], v[24:27]
	s_nop 2
	ds_read2_b64 v[22:25], v111 offset0:48 offset1:52
	s_waitcnt lgkmcnt(1)
	v_mfma_f32_16x16x32_bf16 v[40:43], v[40:43], v[46:49], v[54:57]
	v_mfma_f32_16x16x32_bf16 v[50:53], v[50:53], v[46:49], v[58:61]
	v_mfma_f32_16x16x32_bf16 v[54:57], v[62:65], v[46:49], v[68:71]
	ds_read2_b64 v[44:47], v113 offset0:48 offset1:56
	s_nop 0
	ds_read2_b64 v[58:61], v146 offset0:48 offset1:56
	ds_read2_b64 v[62:65], v148 offset0:48 offset1:56
	ds_read2_b64 v[66:69], v149 offset0:48 offset1:56
	s_waitcnt lgkmcnt(3)
	v_mov_b32_e32 v26, v44
	v_mfma_f32_16x16x32_bf16 v[22:25], v[22:25], v[10:13], v[28:31]
	v_mov_b32_e32 v27, v45
	s_waitcnt lgkmcnt(2)
	s_nop 0
	v_mov_b32_e32 v28, v58
	v_mov_b32_e32 v29, v59
	s_nop 1
	v_mfma_f32_16x16x32_bf16 v[32:35], v[26:29], v[10:13], v[32:35]
	s_waitcnt lgkmcnt(1)
	v_mov_b32_e32 v26, v62
	v_mov_b32_e32 v27, v63
	s_waitcnt lgkmcnt(0)
	v_mov_b32_e32 v28, v66
	v_mov_b32_e32 v29, v67
	v_mov_b32_e32 v66, v64
	v_mov_b32_e32 v67, v65
	v_mfma_f32_16x16x32_bf16 v[36:39], v[26:29], v[10:13], v[36:39]
	ds_read2_b64 v[26:29], v150 offset0:56 offset1:60
	s_waitcnt lgkmcnt(0)
	v_mfma_f32_16x16x32_bf16 v[40:43], v[26:29], v[10:13], v[40:43]
	ds_read2_b64 v[26:29], v151 offset0:56 offset1:60
	ds_read2_b64 v[70:73], v152 offset0:48 offset1:56
	ds_read2_b64 v[82:85], v153 offset0:48 offset1:56
	s_waitcnt lgkmcnt(2)
	v_mfma_f32_16x16x32_bf16 v[48:51], v[26:29], v[10:13], v[50:53]
	s_waitcnt lgkmcnt(1)
	v_mov_b32_e32 v26, v72
	v_mov_b32_e32 v27, v73
	s_waitcnt lgkmcnt(0)
	v_mov_b32_e32 v28, v84
	v_mov_b32_e32 v29, v85
	v_mov_b32_e32 v72, v82
	v_mov_b32_e32 v73, v83
	v_mfma_f32_16x16x32_bf16 v[52:55], v[26:29], v[10:13], v[54:57]
	s_nop 2
	ds_read2_b64 v[56:59], v154 offset0:48 offset1:56
	ds_read2_b64 v[130:133], v155 offset0:48 offset1:56
	ds_read2_b64 v[4:7], v107 offset0:56 offset1:60
	s_waitcnt lgkmcnt(2)
	v_mov_b32_e32 v26, v58
	v_mov_b32_e32 v27, v59
	s_waitcnt lgkmcnt(1)
	v_mov_b32_e32 v28, v132
	v_mov_b32_e32 v29, v133
	v_mov_b32_e32 v58, v46
	v_mov_b32_e32 v59, v47
	v_mfma_f32_16x16x32_bf16 v[132:135], v[26:29], v[10:13], v[18:21]
	s_waitcnt lgkmcnt(0)
	v_mfma_f32_16x16x32_bf16 v[28:31], v[4:7], v[0:3], v[14:17]
	ds_read2_b64 v[4:7], v111 offset0:56 offset1:60
	s_waitcnt lgkmcnt(0)
	v_mfma_f32_16x16x32_bf16 v[24:27], v[4:7], v[0:3], v[22:25]
	ds_read2_b64 v[4:7], v150 offset0:48 offset1:52
	s_waitcnt lgkmcnt(0)
	v_mfma_f32_16x16x32_bf16 v[12:15], v[4:7], v[0:3], v[40:43]
	ds_read2_b64 v[4:7], v151 offset0:48 offset1:52
	v_mfma_f32_16x16x32_bf16 v[20:23], v[58:61], v[0:3], v[32:35]
	v_mov_b32_e32 v58, v130
	v_mov_b32_e32 v59, v131
	v_mfma_f32_16x16x32_bf16 v[16:19], v[66:69], v[0:3], v[36:39]
	s_waitcnt lgkmcnt(0)
	v_mfma_f32_16x16x32_bf16 v[8:11], v[4:7], v[0:3], v[48:51]
	v_mfma_f32_16x16x32_bf16 v[4:7], v[70:73], v[0:3], v[52:55]
	v_mfma_f32_16x16x32_bf16 v[0:3], v[56:59], v[0:3], v[132:135]
	s_and_saveexec_b64 s[0:1], s[4:5]
	s_cbranch_execz .LBB0_691
	v_bfe_u32 v34, v28, 16, 1
	v_readlane_b32 s4, v255, 24
	v_add3_u32 v28, v28, v34, s74
	v_bfe_u32 v34, v29, 16, 1
	v_readlane_b32 s5, v255, 25
	v_lshrrev_b32_e32 v28, 16, v28
	v_add3_u32 v29, v29, v34, s74
	s_lshl_b32 s22, s33, 7
	v_mov_b64_e32 v[32:33], s[4:5]
	v_and_or_b32 v28, v29, s73, v28
	v_bfe_u32 v29, v30, 16, 1
	v_mad_u64_u32 v[32:33], s[18:19], v78, s87, v[32:33]
	s_lshl_b32 s80, s22, 1
	v_add3_u32 v29, v30, v29, s74
	v_bfe_u32 v30, v31, 16, 1
	v_lshl_add_u64 v[32:33], v[32:33], 0, s[80:81]
	v_lshrrev_b32_e32 v29, 16, v29
	v_add3_u32 v30, v31, v30, s74
	v_lshl_add_u64 v[32:33], v[90:91], 1, v[32:33]
	v_and_or_b32 v29, v30, s73, v29
	global_store_dwordx2 v[32:33], v[28:29], off offset:2048
	v_bfe_u32 v28, v24, 16, 1
	v_add3_u32 v24, v24, v28, s74
	v_bfe_u32 v28, v25, 16, 1
	v_lshrrev_b32_e32 v24, 16, v24
	v_add3_u32 v25, v25, v28, s74
	v_and_or_b32 v24, v25, s73, v24
	v_bfe_u32 v25, v26, 16, 1
	v_add3_u32 v25, v26, v25, s74
	v_bfe_u32 v26, v27, 16, 1
	v_lshrrev_b32_e32 v25, 16, v25
	v_add3_u32 v26, v27, v26, s74
	v_and_or_b32 v25, v26, s73, v25
	global_store_dwordx2 v[32:33], v[24:25], off offset:2080
	v_bfe_u32 v24, v20, 16, 1
	v_add3_u32 v20, v20, v24, s74
	v_bfe_u32 v24, v21, 16, 1
	v_lshrrev_b32_e32 v20, 16, v20
	v_add3_u32 v21, v21, v24, s74
	v_and_or_b32 v20, v21, s73, v20
	v_bfe_u32 v21, v22, 16, 1
	v_add3_u32 v21, v22, v21, s74
	v_bfe_u32 v22, v23, 16, 1
	v_lshrrev_b32_e32 v21, 16, v21
	v_add3_u32 v22, v23, v22, s74
	v_and_or_b32 v21, v22, s73, v21
	global_store_dwordx2 v[32:33], v[20:21], off offset:2112
	v_bfe_u32 v20, v16, 16, 1
	v_add3_u32 v16, v16, v20, s74
	v_bfe_u32 v20, v17, 16, 1
	v_lshrrev_b32_e32 v16, 16, v16
	v_add3_u32 v17, v17, v20, s74
	v_and_or_b32 v16, v17, s73, v16
	v_bfe_u32 v17, v18, 16, 1
	v_add3_u32 v17, v18, v17, s74
	v_bfe_u32 v18, v19, 16, 1
	v_lshrrev_b32_e32 v17, 16, v17
	v_add3_u32 v18, v19, v18, s74
	v_and_or_b32 v17, v18, s73, v17
	global_store_dwordx2 v[32:33], v[16:17], off offset:2144
	v_bfe_u32 v16, v12, 16, 1
	v_add3_u32 v12, v12, v16, s74
	v_bfe_u32 v16, v13, 16, 1
	v_lshrrev_b32_e32 v12, 16, v12
	v_add3_u32 v13, v13, v16, s74
	v_and_or_b32 v12, v13, s73, v12
	v_bfe_u32 v13, v14, 16, 1
	v_add3_u32 v13, v14, v13, s74
	v_bfe_u32 v14, v15, 16, 1
	v_lshrrev_b32_e32 v13, 16, v13
	v_add3_u32 v14, v15, v14, s74
	v_and_or_b32 v13, v14, s73, v13
	global_store_dwordx2 v[32:33], v[12:13], off offset:2176
	v_bfe_u32 v12, v8, 16, 1
	v_add3_u32 v8, v8, v12, s74
	v_bfe_u32 v12, v9, 16, 1
	v_lshrrev_b32_e32 v8, 16, v8
	v_add3_u32 v9, v9, v12, s74
	v_and_or_b32 v8, v9, s73, v8
	v_bfe_u32 v9, v10, 16, 1
	v_add3_u32 v9, v10, v9, s74
	v_bfe_u32 v10, v11, 16, 1
	v_lshrrev_b32_e32 v9, 16, v9
	v_add3_u32 v10, v11, v10, s74
	v_and_or_b32 v9, v10, s73, v9
	global_store_dwordx2 v[32:33], v[8:9], off offset:2208
	v_bfe_u32 v8, v4, 16, 1
	v_add3_u32 v4, v4, v8, s74
	v_bfe_u32 v8, v5, 16, 1
	v_lshrrev_b32_e32 v4, 16, v4
	v_add3_u32 v5, v5, v8, s74
	v_and_or_b32 v4, v5, s73, v4
	v_bfe_u32 v5, v6, 16, 1
	v_add3_u32 v5, v6, v5, s74
	v_bfe_u32 v6, v7, 16, 1
	v_lshrrev_b32_e32 v5, 16, v5
	v_add3_u32 v6, v7, v6, s74
	v_and_or_b32 v5, v6, s73, v5
	global_store_dwordx2 v[32:33], v[4:5], off offset:2240
	v_bfe_u32 v4, v0, 16, 1
	v_add3_u32 v0, v0, v4, s74
	v_bfe_u32 v4, v1, 16, 1
	v_lshrrev_b32_e32 v0, 16, v0
	v_add3_u32 v1, v1, v4, s74
	v_and_or_b32 v0, v1, s73, v0
	v_bfe_u32 v1, v2, 16, 1
	v_add3_u32 v1, v2, v1, s74
	v_bfe_u32 v2, v3, 16, 1
	v_lshrrev_b32_e32 v1, 16, v1
	v_add3_u32 v2, v3, v2, s74
	v_and_or_b32 v1, v2, s73, v1
	global_store_dwordx2 v[32:33], v[0:1], off offset:2272

.LBB0_1839:
	s_andn2_b64 vcc, exec, s[0:1]
	s_cbranch_vccnz .LBB0_1845
	v_lshrrev_b32_e32 v0, 2, v38
	v_add_u32_e32 v78, 0x80, v0
	s_and_b32 s33, s10, 3
	v_lshlrev_b64 v[0:1], 10, v[78:79]
	v_or_b32_e32 v0, s33, v0
	v_readlane_b32 s52, v254, 3
	v_or_b32_e32 v2, v0, v92
	v_mov_b32_e32 v3, v1
	v_readlane_b32 s53, v254, 4
	v_readlane_b32 s54, v254, 5
	v_readlane_b32 s55, v254, 6
	v_readlane_b32 s56, v254, 7
	v_readlane_b32 s57, v254, 8
	v_readlane_b32 s58, v254, 9
	v_readlane_b32 s59, v254, 10
	v_readlane_b32 s60, v254, 11
	v_readlane_b32 s61, v254, 12
	v_readlane_b32 s62, v254, 13
	v_readlane_b32 s63, v254, 14
	v_or_b32_e32 v18, v0, v94
	v_mov_b32_e32 v19, v1
	v_or_b32_e32 v34, v0, v96
	v_mov_b32_e32 v35, v1
	v_or_b32_e32 v52, v0, v98
	v_mov_b32_e32 v53, v1
	v_lshlrev_b64 v[10:11], 9, v[2:3]
	v_lshlrev_b32_e32 v39, 2, v84
	v_readlane_b32 s64, v254, 15
	v_readlane_b32 s65, v254, 16
	v_readlane_b32 s66, v254, 17
	v_readlane_b32 s67, v254, 18
	s_mov_b64 s[52:53], s[56:57]
	v_lshlrev_b64 v[26:27], 9, v[18:19]
	v_lshlrev_b64 v[44:45], 9, v[34:35]
	v_lshlrev_b64 v[60:61], 9, v[52:53]
	v_or_b32_e32 v10, v10, v39
	s_mov_b64 s[54:55], s[58:59]
	s_mov_b64 s[56:57], s[60:61]
	s_mov_b64 s[58:59], s[62:63]
	s_mov_b64 s[60:61], s[64:65]
	s_mov_b64 s[62:63], s[66:67]
	v_or_b32_e32 v26, v26, v39
	v_or_b32_e32 v44, v44, v39
	v_or_b32_e32 v60, v60, v39
	v_lshl_add_u64 v[6:7], s[60:61], 0, v[10:11]
	v_lshl_add_u64 v[14:15], s[62:63], 0, v[10:11]
	v_lshl_add_u64 v[22:23], s[60:61], 0, v[26:27]
	v_lshl_add_u64 v[30:31], s[62:63], 0, v[26:27]
	s_waitcnt vmcnt(2)
	v_lshl_add_u64 v[40:41], s[60:61], 0, v[44:45]
	v_lshl_add_u64 v[48:49], s[62:63], 0, v[44:45]
	v_lshl_add_u64 v[56:57], s[60:61], 0, v[60:61]
	v_lshl_add_u64 v[64:65], s[62:63], 0, v[60:61]
	global_load_dwordx4 v[2:5], v[6:7], off offset:16
	s_nop 0
	global_load_dwordx4 v[6:9], v[6:7], off
	s_nop 0
	global_load_dwordx4 v[10:13], v[14:15], off offset:16
	s_nop 0
	global_load_dwordx4 v[14:17], v[14:15], off
	s_nop 0
	global_load_dwordx4 v[18:21], v[22:23], off offset:16
	s_nop 0
	global_load_dwordx4 v[22:25], v[22:23], off
	s_nop 0
	global_load_dwordx4 v[26:29], v[30:31], off offset:16
	s_nop 0
	global_load_dwordx4 v[30:33], v[30:31], off
	s_nop 0
	global_load_dwordx4 v[34:37], v[40:41], off offset:16
	s_nop 0
	global_load_dwordx4 v[40:43], v[40:41], off
	s_nop 0
	global_load_dwordx4 v[44:47], v[48:49], off offset:16
	s_nop 0
	global_load_dwordx4 v[48:51], v[48:49], off
	s_nop 0
	global_load_dwordx4 v[52:55], v[56:57], off offset:16
	s_nop 0
	global_load_dwordx4 v[56:59], v[56:57], off
	s_nop 0
	global_load_dwordx4 v[60:63], v[64:65], off offset:16
	s_nop 0
	global_load_dwordx4 v[64:67], v[64:65], off
	v_or_b32_e32 v70, v0, v100
	v_mov_b32_e32 v71, v1
	v_or_b32_e32 v136, v0, v102
	v_mov_b32_e32 v137, v1
	v_or_b32_e32 v218, v0, v104
	v_mov_b32_e32 v219, v1
	v_lshl_add_u64 v[74:75], v[0:1], 0, v[106:107]
	v_lshlrev_b64 v[128:129], 9, v[70:71]
	v_lshlrev_b64 v[210:211], 9, v[136:137]
	v_lshlrev_b64 v[226:227], 9, v[218:219]
	v_lshlrev_b64 v[74:75], 9, v[74:75]
	v_or_b32_e32 v128, v128, v39
	v_or_b32_e32 v210, v210, v39
	v_or_b32_e32 v226, v226, v39
	v_or_b32_e32 v74, v74, v39
	v_lshl_add_u64 v[114:115], s[60:61], 0, v[128:129]
	v_lshl_add_u64 v[132:133], s[62:63], 0, v[128:129]
	v_lshl_add_u64 v[140:141], s[60:61], 0, v[210:211]
	v_lshl_add_u64 v[214:215], s[62:63], 0, v[210:211]
	v_lshl_add_u64 v[222:223], s[60:61], 0, v[226:227]
	v_lshl_add_u64 v[230:231], s[62:63], 0, v[226:227]
	v_lshl_add_u64 v[238:239], s[60:61], 0, v[74:75]
	v_lshl_add_u64 v[74:75], s[62:63], 0, v[74:75]
	global_load_dwordx4 v[70:73], v[114:115], off offset:16
	s_nop 0
	global_load_dwordx4 v[114:117], v[114:115], off
	s_nop 0
	global_load_dwordx4 v[128:131], v[132:133], off offset:16
	s_nop 0
	global_load_dwordx4 v[132:135], v[132:133], off
	s_nop 0
	global_load_dwordx4 v[136:139], v[140:141], off offset:16
	s_nop 0
	global_load_dwordx4 v[140:143], v[140:141], off
	s_nop 0
	global_load_dwordx4 v[210:213], v[214:215], off offset:16
	s_nop 0
	global_load_dwordx4 v[214:217], v[214:215], off
	s_nop 0
	global_load_dwordx4 v[218:221], v[222:223], off offset:16
	s_nop 0
	global_load_dwordx4 v[222:225], v[222:223], off
	s_nop 0
	global_load_dwordx4 v[226:229], v[230:231], off offset:16
	s_nop 0
	global_load_dwordx4 v[230:233], v[230:231], off
	s_nop 0
	global_load_dwordx4 v[234:237], v[238:239], off offset:16
	s_nop 0
	global_load_dwordx4 v[238:241], v[238:239], off
	s_nop 0
	global_load_dwordx4 v[242:245], v[74:75], off offset:16
	global_load_dwordx4 v[246:249], v[74:75], off
	s_waitcnt vmcnt(30)
	v_bfe_u32 v68, v6, 16, 1
	v_add3_u32 v6, v6, v68, s90
	v_bfe_u32 v68, v7, 16, 1
	v_lshrrev_b32_e32 v6, 16, v6
	v_add3_u32 v7, v7, v68, s90
	v_and_or_b32 v6, v7, s87, v6
	v_bfe_u32 v7, v8, 16, 1
	v_add3_u32 v7, v8, v7, s90
	v_bfe_u32 v8, v9, 16, 1
	v_lshrrev_b32_e32 v7, 16, v7
	v_add3_u32 v8, v9, v8, s90
	v_and_or_b32 v7, v8, s87, v7
	v_bfe_u32 v8, v2, 16, 1
	v_add3_u32 v2, v2, v8, s90
	v_bfe_u32 v8, v3, 16, 1
	v_lshrrev_b32_e32 v2, 16, v2
	v_add3_u32 v3, v3, v8, s90
	v_and_or_b32 v8, v3, s87, v2
	v_bfe_u32 v2, v4, 16, 1
	v_add3_u32 v2, v4, v2, s90
	v_bfe_u32 v3, v5, 16, 1
	v_lshrrev_b32_e32 v2, 16, v2
	v_add3_u32 v3, v5, v3, s90
	v_and_or_b32 v9, v3, s87, v2
	s_waitcnt vmcnt(28)
	v_bfe_u32 v2, v14, 16, 1
	v_add3_u32 v2, v14, v2, s90
	v_bfe_u32 v14, v10, 16, 1
	v_add3_u32 v10, v10, v14, s90
	v_bfe_u32 v14, v11, 16, 1
	v_add3_u32 v11, v11, v14, s90
	v_bfe_u32 v14, v12, 16, 1
	v_add3_u32 v12, v12, v14, s90
	v_bfe_u32 v14, v13, 16, 1
	v_bfe_u32 v3, v15, 16, 1
	v_bfe_u32 v4, v16, 16, 1
	v_bfe_u32 v5, v17, 16, 1
	v_add3_u32 v13, v13, v14, s90
	v_add_u32_e32 v14, v83, v163
	v_add3_u32 v3, v15, v3, s90
	v_add3_u32 v4, v16, v4, s90
	v_add3_u32 v5, v17, v5, s90
	ds_write_b128 v14, v[6:9]
	ds_write_b16_d16_hi v164, v2
	ds_write_b16_d16_hi v164, v3 offset:528
	ds_write_b16_d16_hi v164, v4 offset:1056
	ds_write_b16_d16_hi v164, v5 offset:1584
	ds_write_b16_d16_hi v164, v10 offset:2112
	ds_write_b16_d16_hi v164, v11 offset:2640
	ds_write_b16_d16_hi v164, v12 offset:3168
	ds_write_b16_d16_hi v164, v13 offset:3696
	s_waitcnt vmcnt(26)
	v_bfe_u32 v2, v22, 16, 1
	v_add3_u32 v2, v22, v2, s90
	v_bfe_u32 v3, v23, 16, 1
	v_lshrrev_b32_e32 v2, 16, v2
	v_add3_u32 v3, v23, v3, s90
	v_and_or_b32 v2, v3, s87, v2
	v_bfe_u32 v3, v24, 16, 1
	v_add3_u32 v3, v24, v3, s90
	v_bfe_u32 v4, v25, 16, 1
	v_lshrrev_b32_e32 v3, 16, v3
	v_add3_u32 v4, v25, v4, s90
	v_and_or_b32 v3, v4, s87, v3
	v_bfe_u32 v4, v18, 16, 1
	v_add3_u32 v4, v18, v4, s90
	v_bfe_u32 v5, v19, 16, 1
	v_lshrrev_b32_e32 v4, 16, v4
	v_add3_u32 v5, v19, v5, s90
	v_and_or_b32 v4, v5, s87, v4
	v_bfe_u32 v5, v20, 16, 1
	v_add3_u32 v5, v20, v5, s90
	v_bfe_u32 v6, v21, 16, 1
	v_lshrrev_b32_e32 v5, 16, v5
	v_add3_u32 v6, v21, v6, s90
	v_and_or_b32 v5, v6, s87, v5
	s_waitcnt vmcnt(24)
	v_bfe_u32 v6, v30, 16, 1
	v_bfe_u32 v7, v31, 16, 1
	v_bfe_u32 v8, v32, 16, 1
	v_bfe_u32 v9, v33, 16, 1
	v_bfe_u32 v10, v26, 16, 1
	v_bfe_u32 v11, v27, 16, 1
	v_bfe_u32 v12, v28, 16, 1
	v_bfe_u32 v13, v29, 16, 1
	v_add_u32_e32 v14, v83, v165
	v_add3_u32 v6, v30, v6, s90
	v_add3_u32 v7, v31, v7, s90
	v_add3_u32 v8, v32, v8, s90
	v_add3_u32 v9, v33, v9, s90
	v_add3_u32 v10, v26, v10, s90
	v_add3_u32 v11, v27, v11, s90
	v_add3_u32 v12, v28, v12, s90
	v_add3_u32 v13, v29, v13, s90
	ds_write_b128 v14, v[2:5]
	ds_write_b16_d16_hi v166, v6
	ds_write_b16_d16_hi v166, v7 offset:528
	ds_write_b16_d16_hi v166, v8 offset:1056
	ds_write_b16_d16_hi v166, v9 offset:1584
	ds_write_b16_d16_hi v166, v10 offset:2112
	ds_write_b16_d16_hi v166, v11 offset:2640
	ds_write_b16_d16_hi v166, v12 offset:3168
	ds_write_b16_d16_hi v166, v13 offset:3696
	s_waitcnt vmcnt(22)
	v_bfe_u32 v2, v40, 16, 1
	v_add3_u32 v2, v40, v2, s90
	v_bfe_u32 v3, v41, 16, 1
	v_lshrrev_b32_e32 v2, 16, v2
	v_add3_u32 v3, v41, v3, s90
	v_and_or_b32 v2, v3, s87, v2
	v_bfe_u32 v3, v42, 16, 1
	v_add3_u32 v3, v42, v3, s90
	v_bfe_u32 v4, v43, 16, 1
	v_lshrrev_b32_e32 v3, 16, v3
	v_add3_u32 v4, v43, v4, s90
	v_and_or_b32 v3, v4, s87, v3
	v_bfe_u32 v4, v34, 16, 1
	v_add3_u32 v4, v34, v4, s90
	v_bfe_u32 v5, v35, 16, 1
	v_lshrrev_b32_e32 v4, 16, v4
	v_add3_u32 v5, v35, v5, s90
	v_and_or_b32 v4, v5, s87, v4
	v_bfe_u32 v5, v36, 16, 1
	v_add3_u32 v5, v36, v5, s90
	v_bfe_u32 v6, v37, 16, 1
	v_lshrrev_b32_e32 v5, 16, v5
	v_add3_u32 v6, v37, v6, s90
	v_and_or_b32 v5, v6, s87, v5
	s_waitcnt vmcnt(20)
	v_bfe_u32 v6, v48, 16, 1
	v_bfe_u32 v7, v49, 16, 1
	v_bfe_u32 v8, v50, 16, 1
	v_bfe_u32 v9, v51, 16, 1
	v_bfe_u32 v10, v44, 16, 1
	v_bfe_u32 v11, v45, 16, 1
	v_bfe_u32 v12, v46, 16, 1
	v_bfe_u32 v13, v47, 16, 1
	v_add3_u32 v6, v48, v6, s90
	v_add3_u32 v7, v49, v7, s90
	v_add3_u32 v8, v50, v8, s90
	v_add3_u32 v9, v51, v9, s90
	v_add3_u32 v10, v44, v10, s90
	v_add3_u32 v11, v45, v11, s90
	v_add3_u32 v12, v46, v12, s90
	v_add3_u32 v13, v47, v13, s90
	ds_write_b128 v197, v[2:5]
	ds_write_b16_d16_hi v180, v6
	ds_write_b16_d16_hi v180, v7 offset:528
	ds_write_b16_d16_hi v180, v8 offset:1056
	ds_write_b16_d16_hi v180, v9 offset:1584
	ds_write_b16_d16_hi v180, v10 offset:2112
	ds_write_b16_d16_hi v180, v11 offset:2640
	ds_write_b16_d16_hi v180, v12 offset:3168
	ds_write_b16_d16_hi v180, v13 offset:3696
	s_waitcnt vmcnt(18)
	v_bfe_u32 v2, v56, 16, 1
	v_add3_u32 v2, v56, v2, s90
	v_bfe_u32 v3, v57, 16, 1
	v_lshrrev_b32_e32 v2, 16, v2
	v_add3_u32 v3, v57, v3, s90
	v_and_or_b32 v2, v3, s87, v2
	v_bfe_u32 v3, v58, 16, 1
	v_add3_u32 v3, v58, v3, s90
	v_bfe_u32 v4, v59, 16, 1
	v_lshrrev_b32_e32 v3, 16, v3
	v_add3_u32 v4, v59, v4, s90
	v_and_or_b32 v3, v4, s87, v3
	v_bfe_u32 v4, v52, 16, 1
	v_add3_u32 v4, v52, v4, s90
	v_bfe_u32 v5, v53, 16, 1
	v_lshrrev_b32_e32 v4, 16, v4
	v_add3_u32 v5, v53, v5, s90
	v_and_or_b32 v4, v5, s87, v4
	v_bfe_u32 v5, v54, 16, 1
	v_add3_u32 v5, v54, v5, s90
	v_bfe_u32 v6, v55, 16, 1
	v_lshrrev_b32_e32 v5, 16, v5
	v_add3_u32 v6, v55, v6, s90
	v_and_or_b32 v5, v6, s87, v5
	s_waitcnt vmcnt(16)
	v_bfe_u32 v6, v64, 16, 1
	v_bfe_u32 v7, v65, 16, 1
	v_bfe_u32 v8, v66, 16, 1
	v_bfe_u32 v9, v67, 16, 1
	v_bfe_u32 v10, v60, 16, 1
	v_bfe_u32 v11, v61, 16, 1
	v_bfe_u32 v12, v62, 16, 1
	v_bfe_u32 v13, v63, 16, 1
	v_add_u32_e32 v14, v83, v168
	v_add3_u32 v6, v64, v6, s90
	v_add3_u32 v7, v65, v7, s90
	v_add3_u32 v8, v66, v8, s90
	v_add3_u32 v9, v67, v9, s90
	v_add3_u32 v10, v60, v10, s90
	v_add3_u32 v11, v61, v11, s90
	v_add3_u32 v12, v62, v12, s90
	v_add3_u32 v13, v63, v13, s90
	ds_write_b128 v14, v[2:5]
	ds_write_b16_d16_hi v169, v6
	ds_write_b16_d16_hi v169, v7 offset:528
	ds_write_b16_d16_hi v169, v8 offset:1056
	ds_write_b16_d16_hi v169, v9 offset:1584
	ds_write_b16_d16_hi v169, v10 offset:2112
	ds_write_b16_d16_hi v169, v11 offset:2640
	ds_write_b16_d16_hi v169, v12 offset:3168
	ds_write_b16_d16_hi v169, v13 offset:3696
	s_waitcnt vmcnt(0)
	v_mov_b64_e32 v[2:3], v[70:71]
	v_mov_b64_e32 v[4:5], v[72:73]
	v_mov_b64_e32 v[6:7], v[114:115]
	v_mov_b64_e32 v[8:9], v[116:117]
	v_mov_b64_e32 v[10:11], v[128:129]
	v_mov_b64_e32 v[12:13], v[130:131]
	v_mov_b64_e32 v[14:15], v[132:133]
	v_mov_b64_e32 v[16:17], v[134:135]
	v_mov_b64_e32 v[18:19], v[136:137]
	v_mov_b64_e32 v[20:21], v[138:139]
	v_mov_b64_e32 v[22:23], v[140:141]
	v_mov_b64_e32 v[24:25], v[142:143]
	v_mov_b64_e32 v[26:27], v[210:211]
	v_mov_b64_e32 v[28:29], v[212:213]
	v_mov_b64_e32 v[30:31], v[214:215]
	v_mov_b64_e32 v[32:33], v[216:217]
	v_mov_b64_e32 v[34:35], v[218:219]
	v_mov_b64_e32 v[36:37], v[220:221]
	v_mov_b64_e32 v[40:41], v[222:223]
	v_mov_b64_e32 v[42:43], v[224:225]
	v_mov_b64_e32 v[44:45], v[226:227]
	v_mov_b64_e32 v[46:47], v[228:229]
	v_mov_b64_e32 v[48:49], v[230:231]
	v_mov_b64_e32 v[50:51], v[232:233]
	v_mov_b64_e32 v[52:53], v[234:235]
	v_mov_b64_e32 v[54:55], v[236:237]
	v_mov_b64_e32 v[56:57], v[238:239]
	v_mov_b64_e32 v[58:59], v[240:241]
	v_mov_b64_e32 v[60:61], v[242:243]
	v_mov_b64_e32 v[62:63], v[244:245]
	v_mov_b64_e32 v[64:65], v[246:247]
	v_mov_b64_e32 v[66:67], v[248:249]
	s_waitcnt vmcnt(14)
	v_bfe_u32 v0, v6, 16, 1
	v_add3_u32 v0, v6, v0, s90
	v_bfe_u32 v1, v7, 16, 1
	v_lshrrev_b32_e32 v0, 16, v0
	v_add3_u32 v1, v7, v1, s90
	v_and_or_b32 v0, v1, s87, v0
	v_bfe_u32 v1, v8, 16, 1
	v_add3_u32 v1, v8, v1, s90
	v_bfe_u32 v6, v9, 16, 1
	v_lshrrev_b32_e32 v1, 16, v1
	v_add3_u32 v6, v9, v6, s90
	v_and_or_b32 v1, v6, s87, v1
	v_bfe_u32 v6, v2, 16, 1
	v_add3_u32 v2, v2, v6, s90
	v_bfe_u32 v6, v3, 16, 1
	v_lshrrev_b32_e32 v2, 16, v2
	v_add3_u32 v3, v3, v6, s90
	v_and_or_b32 v2, v3, s87, v2
	v_bfe_u32 v3, v4, 16, 1
	v_add3_u32 v3, v4, v3, s90
	v_bfe_u32 v4, v5, 16, 1
	v_lshrrev_b32_e32 v3, 16, v3
	v_add3_u32 v4, v5, v4, s90
	s_waitcnt vmcnt(13)
	v_bfe_u32 v8, v10, 16, 1
	v_bfe_u32 v9, v11, 16, 1
	v_and_or_b32 v3, v4, s87, v3
	s_waitcnt vmcnt(12)
	v_bfe_u32 v4, v14, 16, 1
	v_bfe_u32 v5, v15, 16, 1
	v_bfe_u32 v6, v16, 16, 1
	v_bfe_u32 v7, v17, 16, 1
	v_add3_u32 v8, v10, v8, s90
	v_add3_u32 v9, v11, v9, s90
	v_bfe_u32 v10, v12, 16, 1
	v_bfe_u32 v11, v13, 16, 1
	v_add3_u32 v4, v14, v4, s90
	v_add3_u32 v5, v15, v5, s90
	v_add3_u32 v6, v16, v6, s90
	v_add3_u32 v7, v17, v7, s90
	v_add3_u32 v10, v12, v10, s90
	v_add3_u32 v11, v13, v11, s90
	ds_write_b128 v198, v[0:3]
	ds_write_b16_d16_hi v181, v4
	ds_write_b16_d16_hi v181, v5 offset:528
	ds_write_b16_d16_hi v181, v6 offset:1056
	ds_write_b16_d16_hi v181, v7 offset:1584
	ds_write_b16_d16_hi v181, v8 offset:2112
	ds_write_b16_d16_hi v181, v9 offset:2640
	ds_write_b16_d16_hi v181, v10 offset:3168
	ds_write_b16_d16_hi v181, v11 offset:3696
	s_waitcnt vmcnt(10)
	v_bfe_u32 v0, v22, 16, 1
	v_add3_u32 v0, v22, v0, s90
	v_bfe_u32 v1, v23, 16, 1
	v_lshrrev_b32_e32 v0, 16, v0
	v_add3_u32 v1, v23, v1, s90
	v_and_or_b32 v0, v1, s87, v0
	v_bfe_u32 v1, v24, 16, 1
	v_add3_u32 v1, v24, v1, s90
	v_bfe_u32 v2, v25, 16, 1
	v_lshrrev_b32_e32 v1, 16, v1
	v_add3_u32 v2, v25, v2, s90
	v_and_or_b32 v1, v2, s87, v1
	v_bfe_u32 v2, v18, 16, 1
	v_add3_u32 v2, v18, v2, s90
	v_bfe_u32 v3, v19, 16, 1
	v_lshrrev_b32_e32 v2, 16, v2
	v_add3_u32 v3, v19, v3, s90
	v_and_or_b32 v2, v3, s87, v2
	v_bfe_u32 v3, v20, 16, 1
	v_add3_u32 v3, v20, v3, s90
	v_bfe_u32 v4, v21, 16, 1
	v_lshrrev_b32_e32 v3, 16, v3
	v_add3_u32 v4, v21, v4, s90
	v_and_or_b32 v3, v4, s87, v3
	s_waitcnt vmcnt(8)
	v_bfe_u32 v4, v30, 16, 1
	v_bfe_u32 v5, v31, 16, 1
	v_bfe_u32 v6, v32, 16, 1
	v_bfe_u32 v7, v33, 16, 1
	v_bfe_u32 v8, v26, 16, 1
	v_bfe_u32 v9, v27, 16, 1
	v_bfe_u32 v10, v28, 16, 1
	v_bfe_u32 v11, v29, 16, 1
	v_add_u32_e32 v12, v83, v171
	v_add3_u32 v4, v30, v4, s90
	v_add3_u32 v5, v31, v5, s90
	v_add3_u32 v6, v32, v6, s90
	v_add3_u32 v7, v33, v7, s90
	v_add3_u32 v8, v26, v8, s90
	v_add3_u32 v9, v27, v9, s90
	v_add3_u32 v10, v28, v10, s90
	v_add3_u32 v11, v29, v11, s90
	ds_write_b128 v12, v[0:3]
	ds_write_b16_d16_hi v172, v4
	ds_write_b16_d16_hi v172, v5 offset:528
	ds_write_b16_d16_hi v172, v6 offset:1056
	ds_write_b16_d16_hi v172, v7 offset:1584
	ds_write_b16_d16_hi v172, v8 offset:2112
	ds_write_b16_d16_hi v172, v9 offset:2640
	ds_write_b16_d16_hi v172, v10 offset:3168
	ds_write_b16_d16_hi v172, v11 offset:3696
	s_waitcnt vmcnt(6)
	v_bfe_u32 v0, v40, 16, 1
	v_add3_u32 v0, v40, v0, s90
	v_bfe_u32 v1, v41, 16, 1
	v_lshrrev_b32_e32 v0, 16, v0
	v_add3_u32 v1, v41, v1, s90
	v_and_or_b32 v0, v1, s87, v0
	v_bfe_u32 v1, v42, 16, 1
	v_add3_u32 v1, v42, v1, s90
	v_bfe_u32 v2, v43, 16, 1
	v_lshrrev_b32_e32 v1, 16, v1
	v_add3_u32 v2, v43, v2, s90
	v_and_or_b32 v1, v2, s87, v1
	v_bfe_u32 v2, v34, 16, 1
	v_add3_u32 v2, v34, v2, s90
	v_bfe_u32 v3, v35, 16, 1
	v_lshrrev_b32_e32 v2, 16, v2
	v_add3_u32 v3, v35, v3, s90
	v_and_or_b32 v2, v3, s87, v2
	v_bfe_u32 v3, v36, 16, 1
	v_add3_u32 v3, v36, v3, s90
	v_bfe_u32 v4, v37, 16, 1
	v_lshrrev_b32_e32 v3, 16, v3
	v_add3_u32 v4, v37, v4, s90
	v_and_or_b32 v3, v4, s87, v3
	s_waitcnt vmcnt(4)
	v_bfe_u32 v4, v48, 16, 1
	v_bfe_u32 v5, v49, 16, 1
	v_bfe_u32 v6, v50, 16, 1
	v_bfe_u32 v7, v51, 16, 1
	v_bfe_u32 v8, v44, 16, 1
	v_bfe_u32 v9, v45, 16, 1
	v_bfe_u32 v10, v46, 16, 1
	v_bfe_u32 v11, v47, 16, 1
	v_add3_u32 v4, v48, v4, s90
	v_add3_u32 v5, v49, v5, s90
	v_add3_u32 v6, v50, v6, s90
	v_add3_u32 v7, v51, v7, s90
	v_add3_u32 v8, v44, v8, s90
	v_add3_u32 v9, v45, v9, s90
	v_add3_u32 v10, v46, v10, s90
	v_add3_u32 v11, v47, v11, s90
	ds_write_b128 v199, v[0:3]
	ds_write_b16_d16_hi v182, v4
	ds_write_b16_d16_hi v182, v5 offset:528
	ds_write_b16_d16_hi v182, v6 offset:1056
	ds_write_b16_d16_hi v182, v7 offset:1584
	ds_write_b16_d16_hi v182, v8 offset:2112
	ds_write_b16_d16_hi v182, v9 offset:2640
	ds_write_b16_d16_hi v182, v10 offset:3168
	ds_write_b16_d16_hi v182, v11 offset:3696
	s_waitcnt vmcnt(2)
	v_bfe_u32 v0, v56, 16, 1
	v_add3_u32 v0, v56, v0, s90
	v_bfe_u32 v1, v57, 16, 1
	v_lshrrev_b32_e32 v0, 16, v0
	v_add3_u32 v1, v57, v1, s90
	v_and_or_b32 v0, v1, s87, v0
	v_bfe_u32 v1, v58, 16, 1
	v_add3_u32 v1, v58, v1, s90
	v_bfe_u32 v2, v59, 16, 1
	v_lshrrev_b32_e32 v1, 16, v1
	v_add3_u32 v2, v59, v2, s90
	v_and_or_b32 v1, v2, s87, v1
	v_bfe_u32 v2, v52, 16, 1
	v_add3_u32 v2, v52, v2, s90
	v_bfe_u32 v3, v53, 16, 1
	v_lshrrev_b32_e32 v2, 16, v2
	v_add3_u32 v3, v53, v3, s90
	v_and_or_b32 v2, v3, s87, v2
	v_bfe_u32 v3, v54, 16, 1
	v_add3_u32 v3, v54, v3, s90
	v_bfe_u32 v4, v55, 16, 1
	v_lshrrev_b32_e32 v3, 16, v3
	v_add3_u32 v4, v55, v4, s90
	v_and_or_b32 v3, v4, s87, v3
	s_waitcnt vmcnt(0)
	v_bfe_u32 v4, v64, 16, 1
	v_bfe_u32 v5, v65, 16, 1
	v_bfe_u32 v6, v66, 16, 1
	v_bfe_u32 v7, v67, 16, 1
	v_bfe_u32 v8, v60, 16, 1
	v_bfe_u32 v9, v61, 16, 1
	v_bfe_u32 v10, v62, 16, 1
	v_bfe_u32 v11, v63, 16, 1
	v_add_u32_e32 v12, v83, v174
	v_add3_u32 v4, v64, v4, s90
	v_add3_u32 v5, v65, v5, s90
	v_add3_u32 v6, v66, v6, s90
	v_add3_u32 v7, v67, v7, s90
	v_add3_u32 v8, v60, v8, s90
	v_add3_u32 v9, v61, v9, s90
	v_add3_u32 v10, v62, v10, s90
	v_add3_u32 v11, v63, v11, s90
	ds_write_b128 v12, v[0:3]
	ds_write_b16_d16_hi v175, v4
	ds_write_b16_d16_hi v175, v5 offset:528
	ds_write_b16_d16_hi v175, v6 offset:1056
	ds_write_b16_d16_hi v175, v7 offset:1584
	ds_write_b16_d16_hi v175, v8 offset:2112
	ds_write_b16_d16_hi v175, v9 offset:2640
	ds_write_b16_d16_hi v175, v10 offset:3168
	ds_write_b16_d16_hi v175, v11 offset:3696
	s_andn2_b64 vcc, exec, s[88:89]
	s_waitcnt lgkmcnt(0)
	s_barrier
	s_cbranch_vccnz .LBB0_1844
	v_and_b32_e32 v0, -4, v38
	v_or_b32_e32 v1, 0x4000, v77
	v_add_u32_e32 v78, v0, v1
	v_mov_b64_e32 v[0:1], s[42:43]
	v_mad_u64_u32 v[0:1], s[0:1], v78, s74, v[0:1]
	s_lshl_b32 s78, s33, 8
	v_lshl_add_u64 v[0:1], v[0:1], 0, s[78:79]
	v_lshl_add_u64 v[0:1], v[86:87], 1, v[0:1]
	global_load_dwordx4 v[72:75], v[0:1], off offset:2560
	global_load_dwordx4 v[68:71], v[0:1], off offset:2624
	global_load_dwordx4 v[64:67], v[0:1], off offset:2688
	global_load_dwordx4 v[20:23], v[0:1], off offset:2752
	v_add_u32_e32 v24, v93, v95
	ds_read_b128 v[0:3], v24
	ds_read_b128 v[4:7], v24 offset:64
	v_add_u32_e32 v25, v93, v97
	s_waitcnt vmcnt(3) lgkmcnt(1)
	v_mfma_f32_16x16x32_bf16 v[0:3], v[0:3], v[72:75], 0
	ds_read_b128 v[26:29], v24 offset:17472
	ds_read_b128 v[30:33], v24 offset:21824
	ds_read_b128 v[12:15], v25 offset:64
	s_waitcnt vmcnt(2) lgkmcnt(3)
	v_mfma_f32_16x16x32_bf16 v[0:3], v[4:7], v[68:71], v[0:3]
	ds_read_b128 v[4:7], v24 offset:128
	ds_read_b128 v[114:117], v24 offset:56640
	ds_read_b128 v[128:131], v24 offset:60992
	s_waitcnt vmcnt(1) lgkmcnt(2)
	v_mfma_f32_16x16x32_bf16 v[0:3], v[4:7], v[64:67], v[0:3]
	ds_read_b128 v[4:7], v24 offset:192
	s_waitcnt vmcnt(0) lgkmcnt(0)
	v_mfma_f32_16x16x32_bf16 v[16:19], v[4:7], v[20:23], v[0:3]
	s_nop 4
	ds_read_b128 v[0:3], v24 offset:4352
	ds_read_b128 v[4:7], v24 offset:4416
	s_waitcnt lgkmcnt(1)
	v_mfma_f32_16x16x32_bf16 v[0:3], v[0:3], v[72:75], 0
	s_waitcnt lgkmcnt(0)
	v_mfma_f32_16x16x32_bf16 v[0:3], v[4:7], v[68:71], v[0:3]
	ds_read_b128 v[4:7], v24 offset:4480
	s_waitcnt lgkmcnt(0)
	v_mfma_f32_16x16x32_bf16 v[0:3], v[4:7], v[64:67], v[0:3]
	ds_read_b128 v[4:7], v24 offset:4544
	s_waitcnt lgkmcnt(0)
	v_mfma_f32_16x16x32_bf16 v[8:11], v[4:7], v[20:23], v[0:3]
	s_nop 4
	ds_read_b128 v[0:3], v24 offset:8704
	ds_read_b128 v[4:7], v24 offset:8768
	s_waitcnt lgkmcnt(1)
	v_mfma_f32_16x16x32_bf16 v[0:3], v[0:3], v[72:75], 0
	s_waitcnt lgkmcnt(0)
	v_mfma_f32_16x16x32_bf16 v[0:3], v[4:7], v[68:71], v[0:3]
	ds_read_b128 v[4:7], v24 offset:8832
	s_waitcnt lgkmcnt(0)
	v_mfma_f32_16x16x32_bf16 v[0:3], v[4:7], v[64:67], v[0:3]
	ds_read_b128 v[4:7], v24 offset:8896
	s_waitcnt lgkmcnt(0)
	v_mfma_f32_16x16x32_bf16 v[0:3], v[4:7], v[20:23], v[0:3]
	ds_read_b128 v[4:7], v25
	s_waitcnt lgkmcnt(0)
	v_mfma_f32_16x16x32_bf16 v[4:7], v[4:7], v[72:75], 0
	v_mfma_f32_16x16x32_bf16 v[4:7], v[12:15], v[68:71], v[4:7]
	ds_read_b128 v[12:15], v25 offset:128
	s_waitcnt lgkmcnt(0)
	v_mfma_f32_16x16x32_bf16 v[4:7], v[12:15], v[64:67], v[4:7]
	ds_read_b128 v[12:15], v25 offset:192
	v_add_u32_e32 v25, v93, v99
	ds_read_b128 v[36:39], v25 offset:64
	s_waitcnt lgkmcnt(1)
	v_mfma_f32_16x16x32_bf16 v[12:15], v[12:15], v[20:23], v[4:7]
	s_nop 2
	ds_read_b128 v[4:7], v24 offset:17408
	s_waitcnt lgkmcnt(0)
	v_mfma_f32_16x16x32_bf16 v[4:7], v[4:7], v[72:75], 0
	v_mfma_f32_16x16x32_bf16 v[4:7], v[26:29], v[68:71], v[4:7]
	ds_read_b128 v[26:29], v24 offset:17536
	s_waitcnt lgkmcnt(0)
	v_mfma_f32_16x16x32_bf16 v[4:7], v[26:29], v[64:67], v[4:7]
	ds_read_b128 v[26:29], v24 offset:17600
	s_waitcnt lgkmcnt(0)
	v_mfma_f32_16x16x32_bf16 v[4:7], v[26:29], v[20:23], v[4:7]
	ds_read_b128 v[26:29], v24 offset:21760
	s_waitcnt lgkmcnt(0)
	v_mfma_f32_16x16x32_bf16 v[26:29], v[26:29], v[72:75], 0
	v_mfma_f32_16x16x32_bf16 v[26:29], v[30:33], v[68:71], v[26:29]
	ds_read_b128 v[30:33], v24 offset:21888
	s_waitcnt lgkmcnt(0)
	v_mfma_f32_16x16x32_bf16 v[26:29], v[30:33], v[64:67], v[26:29]
	ds_read_b128 v[30:33], v24 offset:21952
	s_waitcnt lgkmcnt(0)
	v_mfma_f32_16x16x32_bf16 v[48:51], v[30:33], v[20:23], v[26:29]
	s_nop 4
	ds_read_b128 v[26:29], v24 offset:26112
	ds_read_b128 v[30:33], v24 offset:26176
	s_waitcnt lgkmcnt(1)
	v_mfma_f32_16x16x32_bf16 v[26:29], v[26:29], v[72:75], 0
	s_waitcnt lgkmcnt(0)
	v_mfma_f32_16x16x32_bf16 v[26:29], v[30:33], v[68:71], v[26:29]
	ds_read_b128 v[30:33], v24 offset:26240
	s_waitcnt lgkmcnt(0)
	v_mfma_f32_16x16x32_bf16 v[26:29], v[30:33], v[64:67], v[26:29]
	ds_read_b128 v[30:33], v24 offset:26304
	s_waitcnt lgkmcnt(0)
	v_mfma_f32_16x16x32_bf16 v[32:35], v[30:33], v[20:23], v[26:29]
	s_nop 4
	ds_read_b128 v[26:29], v25
	s_waitcnt lgkmcnt(0)
	v_mfma_f32_16x16x32_bf16 v[26:29], v[26:29], v[72:75], 0
	v_mfma_f32_16x16x32_bf16 v[26:29], v[36:39], v[68:71], v[26:29]
	ds_read_b128 v[36:39], v25 offset:128
	s_waitcnt lgkmcnt(0)
	v_mfma_f32_16x16x32_bf16 v[26:29], v[36:39], v[64:67], v[26:29]
	ds_read_b128 v[36:39], v25 offset:192
	v_add_u32_e32 v25, v93, v101
	s_waitcnt lgkmcnt(0)
	v_mfma_f32_16x16x32_bf16 v[60:63], v[36:39], v[20:23], v[26:29]
	s_nop 3
	ds_read_b128 v[26:29], v24 offset:34816
	ds_read_b128 v[36:39], v24 offset:34880
	s_waitcnt lgkmcnt(1)
	v_mfma_f32_16x16x32_bf16 v[26:29], v[26:29], v[72:75], 0
	s_waitcnt lgkmcnt(0)
	v_mfma_f32_16x16x32_bf16 v[26:29], v[36:39], v[68:71], v[26:29]
	ds_read_b128 v[36:39], v24 offset:34944
	s_waitcnt lgkmcnt(0)
	v_mfma_f32_16x16x32_bf16 v[26:29], v[36:39], v[64:67], v[26:29]
	ds_read_b128 v[36:39], v24 offset:35008
	s_waitcnt lgkmcnt(0)
	v_mfma_f32_16x16x32_bf16 v[56:59], v[36:39], v[20:23], v[26:29]
	s_nop 4
	ds_read_b128 v[26:29], v24 offset:39168
	ds_read_b128 v[36:39], v24 offset:39232
	s_waitcnt lgkmcnt(1)
	v_mfma_f32_16x16x32_bf16 v[26:29], v[26:29], v[72:75], 0
	s_waitcnt lgkmcnt(0)
	v_mfma_f32_16x16x32_bf16 v[26:29], v[36:39], v[68:71], v[26:29]
	ds_read_b128 v[36:39], v24 offset:39296
	s_waitcnt lgkmcnt(0)
	v_mfma_f32_16x16x32_bf16 v[26:29], v[36:39], v[64:67], v[26:29]
	ds_read_b128 v[36:39], v24 offset:39360
	s_waitcnt lgkmcnt(0)
	v_mfma_f32_16x16x32_bf16 v[52:55], v[36:39], v[20:23], v[26:29]
	s_nop 4
	ds_read_b128 v[26:29], v24 offset:43520
	ds_read_b128 v[36:39], v24 offset:43584
	s_waitcnt lgkmcnt(1)
	v_mfma_f32_16x16x32_bf16 v[26:29], v[26:29], v[72:75], 0
	s_waitcnt lgkmcnt(0)
	v_mfma_f32_16x16x32_bf16 v[26:29], v[36:39], v[68:71], v[26:29]
	ds_read_b128 v[36:39], v24 offset:43648
	s_waitcnt lgkmcnt(0)
	v_mfma_f32_16x16x32_bf16 v[26:29], v[36:39], v[64:67], v[26:29]
	ds_read_b128 v[36:39], v24 offset:43712
	s_waitcnt lgkmcnt(0)
	v_mfma_f32_16x16x32_bf16 v[44:47], v[36:39], v[20:23], v[26:29]
	s_nop 4
	ds_read_b128 v[26:29], v25
	ds_read_b128 v[36:39], v25 offset:64
	s_waitcnt lgkmcnt(1)
	v_mfma_f32_16x16x32_bf16 v[26:29], v[26:29], v[72:75], 0
	s_waitcnt lgkmcnt(0)
	v_mfma_f32_16x16x32_bf16 v[26:29], v[36:39], v[68:71], v[26:29]
	ds_read_b128 v[36:39], v25 offset:128
	s_waitcnt lgkmcnt(0)
	v_mfma_f32_16x16x32_bf16 v[26:29], v[36:39], v[64:67], v[26:29]
	ds_read_b128 v[36:39], v25 offset:192
	s_waitcnt lgkmcnt(0)
	v_mfma_f32_16x16x32_bf16 v[40:43], v[36:39], v[20:23], v[26:29]
	s_nop 4
	ds_read_b128 v[26:29], v24 offset:52224
	ds_read_b128 v[36:39], v24 offset:52288
	s_waitcnt lgkmcnt(1)
	v_mfma_f32_16x16x32_bf16 v[26:29], v[26:29], v[72:75], 0
	s_waitcnt lgkmcnt(0)
	v_mfma_f32_16x16x32_bf16 v[26:29], v[36:39], v[68:71], v[26:29]
	ds_read_b128 v[36:39], v24 offset:52352
	s_waitcnt lgkmcnt(0)
	v_mfma_f32_16x16x32_bf16 v[26:29], v[36:39], v[64:67], v[26:29]
	ds_read_b128 v[36:39], v24 offset:52416
	s_waitcnt lgkmcnt(0)
	v_mfma_f32_16x16x32_bf16 v[36:39], v[36:39], v[20:23], v[26:29]
	s_nop 4
	ds_read_b128 v[26:29], v24 offset:56576
	s_waitcnt lgkmcnt(0)
	v_mfma_f32_16x16x32_bf16 v[26:29], v[26:29], v[72:75], 0
	v_mfma_f32_16x16x32_bf16 v[26:29], v[114:117], v[68:71], v[26:29]
	ds_read_b128 v[114:117], v24 offset:56704
	s_waitcnt lgkmcnt(0)
	v_mfma_f32_16x16x32_bf16 v[26:29], v[114:117], v[64:67], v[26:29]
	ds_read_b128 v[114:117], v24 offset:56768
	s_waitcnt lgkmcnt(0)
	v_mfma_f32_16x16x32_bf16 v[28:31], v[114:117], v[20:23], v[26:29]
	ds_read_b128 v[114:117], v24 offset:60928
	s_waitcnt lgkmcnt(0)
	v_mfma_f32_16x16x32_bf16 v[114:117], v[114:117], v[72:75], 0
	v_mfma_f32_16x16x32_bf16 v[114:117], v[128:131], v[68:71], v[114:117]
	ds_read_b128 v[128:131], v24 offset:61056
	ds_read_b128 v[24:27], v24 offset:61120
	s_waitcnt lgkmcnt(1)
	v_mfma_f32_16x16x32_bf16 v[114:117], v[128:131], v[64:67], v[114:117]
	v_add_u32_e32 v128, v93, v103
	s_waitcnt lgkmcnt(0)
	v_mfma_f32_16x16x32_bf16 v[24:27], v[24:27], v[20:23], v[114:117]
	s_nop 4
	ds_read_b128 v[114:117], v128
	s_waitcnt lgkmcnt(0)
	v_mfma_f32_16x16x32_bf16 v[72:75], v[114:117], v[72:75], 0
	ds_read_b128 v[114:117], v128 offset:64
	s_waitcnt lgkmcnt(0)
	v_mfma_f32_16x16x32_bf16 v[68:71], v[114:117], v[68:71], v[72:75]
	s_nop 4
	ds_read_b128 v[72:75], v128 offset:128
	s_waitcnt lgkmcnt(0)
	v_mfma_f32_16x16x32_bf16 v[64:67], v[72:75], v[64:67], v[68:71]
	s_nop 2
	ds_read_b128 v[68:71], v128 offset:192
	s_waitcnt lgkmcnt(0)
	v_mfma_f32_16x16x32_bf16 v[20:23], v[68:71], v[20:23], v[64:67]
	s_nop 2
	v_mul_f32_e32 v64, 0x3db504f3, v16
	v_mul_f32_e32 v65, 0x3db504f3, v17
	v_max3_f32 v64, v64, s13, v65
	v_mul_f32_e32 v65, 0x3db504f3, v18
	v_mul_f32_e32 v66, 0x3db504f3, v19
	v_max3_f32 v64, v64, v65, v66
	v_mul_f32_e32 v65, 0x3db504f3, v8
	v_mul_f32_e32 v66, 0x3db504f3, v9
	v_max3_f32 v64, v64, v65, v66
	v_mul_f32_e32 v65, 0x3db504f3, v10
	v_mul_f32_e32 v66, 0x3db504f3, v11
	v_max3_f32 v64, v64, v65, v66
	v_mul_f32_e32 v65, 0x3db504f3, v0
	v_mul_f32_e32 v66, 0x3db504f3, v1
	v_max3_f32 v64, v64, v65, v66
	v_mul_f32_e32 v65, 0x3db504f3, v2
	v_mul_f32_e32 v66, 0x3db504f3, v3
	v_max3_f32 v64, v64, v65, v66
	v_mul_f32_e32 v65, 0x3db504f3, v12
	v_mul_f32_e32 v66, 0x3db504f3, v13
	v_max3_f32 v64, v64, v65, v66
	v_mul_f32_e32 v65, 0x3db504f3, v14
	v_mul_f32_e32 v66, 0x3db504f3, v15
	v_max3_f32 v64, v64, v65, v66
	v_mul_f32_e32 v65, 0x3db504f3, v4
	v_mul_f32_e32 v66, 0x3db504f3, v5
	v_max3_f32 v64, v64, v65, v66
	v_mul_f32_e32 v65, 0x3db504f3, v6
	v_mul_f32_e32 v66, 0x3db504f3, v7
	v_max3_f32 v64, v64, v65, v66
	v_mul_f32_e32 v65, 0x3db504f3, v48
	v_mul_f32_e32 v66, 0x3db504f3, v49
	v_max3_f32 v64, v64, v65, v66
	v_mul_f32_e32 v65, 0x3db504f3, v50
	v_mul_f32_e32 v66, 0x3db504f3, v51
	v_max3_f32 v64, v64, v65, v66
	v_mul_f32_e32 v65, 0x3db504f3, v32
	v_mul_f32_e32 v66, 0x3db504f3, v33
	v_max3_f32 v64, v64, v65, v66
	v_mul_f32_e32 v65, 0x3db504f3, v34
	v_mul_f32_e32 v66, 0x3db504f3, v35
	v_max3_f32 v64, v64, v65, v66
	v_mul_f32_e32 v65, 0x3db504f3, v60
	v_mul_f32_e32 v66, 0x3db504f3, v61
	v_max3_f32 v64, v64, v65, v66
	v_mul_f32_e32 v65, 0x3db504f3, v62
	v_mul_f32_e32 v66, 0x3db504f3, v63
	v_max3_f32 v64, v64, v65, v66
	v_mul_f32_e32 v65, 0x3db504f3, v56
	v_mul_f32_e32 v66, 0x3db504f3, v57
	v_max3_f32 v64, v64, v65, v66
	v_mul_f32_e32 v65, 0x3db504f3, v58
	v_mul_f32_e32 v66, 0x3db504f3, v59
	v_max3_f32 v64, v64, v65, v66
	v_mul_f32_e32 v65, 0x3db504f3, v52
	v_mul_f32_e32 v66, 0x3db504f3, v53
	v_max3_f32 v64, v64, v65, v66
	v_mul_f32_e32 v65, 0x3db504f3, v54
	v_mul_f32_e32 v66, 0x3db504f3, v55
	v_max3_f32 v64, v64, v65, v66
	v_mul_f32_e32 v65, 0x3db504f3, v44
	v_mul_f32_e32 v66, 0x3db504f3, v45
	v_max3_f32 v64, v64, v65, v66
	v_mul_f32_e32 v65, 0x3db504f3, v46
	v_mul_f32_e32 v66, 0x3db504f3, v47
	v_max3_f32 v64, v64, v65, v66
	v_mul_f32_e32 v65, 0x3db504f3, v40
	v_mul_f32_e32 v66, 0x3db504f3, v41
	v_max3_f32 v64, v64, v65, v66
	v_mul_f32_e32 v65, 0x3db504f3, v42
	v_mul_f32_e32 v66, 0x3db504f3, v43
	v_max3_f32 v64, v64, v65, v66
	v_mul_f32_e32 v65, 0x3db504f3, v36
	v_mul_f32_e32 v66, 0x3db504f3, v37
	v_max3_f32 v64, v64, v65, v66
	v_mul_f32_e32 v65, 0x3db504f3, v38
	v_mul_f32_e32 v66, 0x3db504f3, v39
	v_max3_f32 v64, v64, v65, v66
	v_mul_f32_e32 v65, 0x3db504f3, v28
	v_mul_f32_e32 v66, 0x3db504f3, v29
	v_max3_f32 v64, v64, v65, v66
	v_mul_f32_e32 v65, 0x3db504f3, v30
	v_mul_f32_e32 v66, 0x3db504f3, v31
	v_max3_f32 v64, v64, v65, v66
	v_mul_f32_e32 v65, 0x3db504f3, v24
	v_mul_f32_e32 v66, 0x3db504f3, v25
	v_max3_f32 v64, v64, v65, v66
	v_mul_f32_e32 v65, 0x3db504f3, v26
	v_mul_f32_e32 v66, 0x3db504f3, v27
	v_max3_f32 v64, v64, v65, v66
	v_mul_f32_e32 v65, 0x3db504f3, v20
	v_mul_f32_e32 v66, 0x3db504f3, v21
	v_max3_f32 v64, v64, v65, v66
	v_mul_f32_e32 v65, 0x3db504f3, v22
	v_mul_f32_e32 v66, 0x3db504f3, v23
	v_max3_f32 v64, v64, v65, v66
	v_and_b32_e32 v66, 64, v200
	v_xor_b32_e32 v65, 16, v200
	v_add_u32_e32 v66, 64, v66
	v_cmp_lt_i32_e32 vcc, v65, v66
	s_nop 1
	v_cndmask_b32_e32 v65, v200, v65, vcc
	v_lshlrev_b32_e32 v210, 2, v65
	ds_bpermute_b32 v65, v210, v64
	s_waitcnt lgkmcnt(0)
	v_max_f32_e32 v65, v65, v65
	v_max_f32_e32 v64, v64, v65
	v_xor_b32_e32 v65, 32, v200
	v_cmp_lt_i32_e32 vcc, v65, v66
	s_nop 1
	v_cndmask_b32_e32 v65, v200, v65, vcc
	v_lshlrev_b32_e32 v211, 2, v65
	ds_bpermute_b32 v65, v211, v64
	s_waitcnt lgkmcnt(0)
	v_max_f32_e32 v65, v65, v65
	v_max_f32_e32 v212, v64, v65
	v_fma_f32 v1, v1, s12, -v212
	v_mul_f32_e32 v1, 0x3fb8aa3b, v1
	v_exp_f32_e32 v129, v1
	v_fma_f32 v1, v2, s12, -v212
	v_mul_f32_e32 v1, 0x3fb8aa3b, v1
	v_exp_f32_e32 v130, v1
	v_fma_f32 v1, v3, s12, -v212
	v_mul_f32_e32 v1, 0x3fb8aa3b, v1
	v_exp_f32_e32 v131, v1
	v_fma_f32 v1, v12, s12, -v212
	v_mul_f32_e32 v1, 0x3fb8aa3b, v1
	v_exp_f32_e32 v132, v1
	v_fma_f32 v1, v13, s12, -v212
	v_mul_f32_e32 v1, 0x3fb8aa3b, v1
	v_exp_f32_e32 v133, v1
	v_fma_f32 v1, v14, s12, -v212
	v_mul_f32_e32 v1, 0x3fb8aa3b, v1
	v_exp_f32_e32 v134, v1
	v_fma_f32 v1, v15, s12, -v212
	v_mul_f32_e32 v1, 0x3fb8aa3b, v1
	v_exp_f32_e32 v135, v1
	v_fma_f32 v1, v4, s12, -v212
	v_mul_f32_e32 v1, 0x3fb8aa3b, v1
	v_exp_f32_e32 v68, v1
	v_fma_f32 v1, v5, s12, -v212
	v_mul_f32_e32 v1, 0x3fb8aa3b, v1
	v_exp_f32_e32 v69, v1
	v_fma_f32 v1, v6, s12, -v212
	v_mul_f32_e32 v1, 0x3fb8aa3b, v1
	v_exp_f32_e32 v70, v1
	v_fma_f32 v1, v7, s12, -v212
	v_mul_f32_e32 v1, 0x3fb8aa3b, v1
	v_exp_f32_e32 v71, v1
	v_fma_f32 v1, v48, s12, -v212
	v_mul_f32_e32 v1, 0x3fb8aa3b, v1
	v_exp_f32_e32 v72, v1
	v_fma_f32 v1, v49, s12, -v212
	v_mul_f32_e32 v1, 0x3fb8aa3b, v1
	v_exp_f32_e32 v73, v1
	v_fma_f32 v1, v50, s12, -v212
	v_mul_f32_e32 v1, 0x3fb8aa3b, v1
	v_exp_f32_e32 v74, v1
	v_fma_f32 v1, v51, s12, -v212
	v_mul_f32_e32 v1, 0x3fb8aa3b, v1
	v_exp_f32_e32 v75, v1
	v_fma_f32 v1, v32, s12, -v212
	v_mul_f32_e32 v1, 0x3fb8aa3b, v1
	v_exp_f32_e32 v64, v1
	v_fma_f32 v1, v33, s12, -v212
	v_mul_f32_e32 v1, 0x3fb8aa3b, v1
	v_exp_f32_e32 v65, v1
	v_fma_f32 v1, v34, s12, -v212
	v_mul_f32_e32 v1, 0x3fb8aa3b, v1
	v_fma_f32 v17, v17, s12, -v212
	v_exp_f32_e32 v66, v1
	v_fma_f32 v1, v35, s12, -v212
	v_fma_f32 v16, v16, s12, -v212
	v_mul_f32_e32 v17, 0x3fb8aa3b, v17
	v_mul_f32_e32 v1, 0x3fb8aa3b, v1
	v_mul_f32_e32 v16, 0x3fb8aa3b, v16
	v_exp_f32_e32 v137, v17
	v_fma_f32 v17, v18, s12, -v212
	v_exp_f32_e32 v67, v1
	v_fma_f32 v1, v60, s12, -v212
	v_exp_f32_e32 v136, v16
	v_mul_f32_e32 v17, 0x3fb8aa3b, v17
	v_mul_f32_e32 v1, 0x3fb8aa3b, v1
	v_exp_f32_e32 v138, v17
	v_fma_f32 v17, v19, s12, -v212
	v_fma_f32 v9, v9, s12, -v212
	v_exp_f32_e32 v60, v1
	v_fma_f32 v1, v61, s12, -v212
	v_mul_f32_e32 v17, 0x3fb8aa3b, v17
	v_fma_f32 v8, v8, s12, -v212
	v_mul_f32_e32 v9, 0x3fb8aa3b, v9
	v_mul_f32_e32 v1, 0x3fb8aa3b, v1
	v_exp_f32_e32 v139, v17
	v_mul_f32_e32 v8, 0x3fb8aa3b, v8
	v_exp_f32_e32 v141, v9
	v_fma_f32 v9, v10, s12, -v212
	v_exp_f32_e32 v61, v1
	v_fma_f32 v1, v62, s12, -v212
	v_add_f32_e32 v16, 0, v136
	v_exp_f32_e32 v140, v8
	v_mul_f32_e32 v9, 0x3fb8aa3b, v9
	v_mul_f32_e32 v1, 0x3fb8aa3b, v1
	v_add_f32_e32 v16, v137, v16
	v_exp_f32_e32 v142, v9
	v_fma_f32 v9, v11, s12, -v212
	v_exp_f32_e32 v62, v1
	v_fma_f32 v1, v63, s12, -v212
	v_add_f32_e32 v16, v138, v16
	v_mul_f32_e32 v9, 0x3fb8aa3b, v9
	v_fma_f32 v0, v0, s12, -v212
	v_mul_f32_e32 v1, 0x3fb8aa3b, v1
	v_add_f32_e32 v16, v139, v16
	v_exp_f32_e32 v143, v9
	v_mul_f32_e32 v0, 0x3fb8aa3b, v0
	v_exp_f32_e32 v63, v1
	v_fma_f32 v1, v56, s12, -v212
	v_add_f32_e32 v8, v140, v16
	v_exp_f32_e32 v128, v0
	v_mul_f32_e32 v1, 0x3fb8aa3b, v1
	v_add_f32_e32 v8, v141, v8
	v_exp_f32_e32 v48, v1
	v_fma_f32 v1, v57, s12, -v212
	v_add_f32_e32 v8, v142, v8
	v_mul_f32_e32 v1, 0x3fb8aa3b, v1
	v_add_f32_e32 v8, v143, v8
	v_exp_f32_e32 v49, v1
	v_fma_f32 v1, v58, s12, -v212
	v_add_f32_e32 v0, v128, v8
	v_mul_f32_e32 v1, 0x3fb8aa3b, v1
	v_add_f32_e32 v0, v129, v0
	v_exp_f32_e32 v50, v1
	v_fma_f32 v1, v59, s12, -v212
	v_add_f32_e32 v0, v130, v0
	v_mul_f32_e32 v1, 0x3fb8aa3b, v1
	v_add_f32_e32 v0, v131, v0
	v_exp_f32_e32 v51, v1
	v_fma_f32 v1, v52, s12, -v212
	v_add_f32_e32 v0, v132, v0
	v_mul_f32_e32 v1, 0x3fb8aa3b, v1
	v_add_f32_e32 v0, v133, v0
	v_exp_f32_e32 v52, v1
	v_fma_f32 v1, v53, s12, -v212
	v_add_f32_e32 v0, v134, v0
	v_mul_f32_e32 v1, 0x3fb8aa3b, v1
	v_add_f32_e32 v0, v135, v0
	v_exp_f32_e32 v53, v1
	v_fma_f32 v1, v54, s12, -v212
	v_add_f32_e32 v0, v68, v0
	v_mul_f32_e32 v1, 0x3fb8aa3b, v1
	v_add_f32_e32 v0, v69, v0
	v_exp_f32_e32 v54, v1
	v_fma_f32 v1, v55, s12, -v212
	v_add_f32_e32 v0, v70, v0
	v_mul_f32_e32 v1, 0x3fb8aa3b, v1
	v_add_f32_e32 v0, v71, v0
	v_exp_f32_e32 v55, v1
	v_fma_f32 v1, v44, s12, -v212
	v_add_f32_e32 v0, v72, v0
	v_mul_f32_e32 v1, 0x3fb8aa3b, v1
	v_add_f32_e32 v0, v73, v0
	v_exp_f32_e32 v18, v1
	v_fma_f32 v1, v45, s12, -v212
	v_add_f32_e32 v0, v74, v0
	v_mul_f32_e32 v1, 0x3fb8aa3b, v1
	v_add_f32_e32 v0, v75, v0
	v_exp_f32_e32 v19, v1
	v_fma_f32 v1, v46, s12, -v212
	v_add_f32_e32 v0, v64, v0
	v_mul_f32_e32 v1, 0x3fb8aa3b, v1
	v_add_f32_e32 v0, v65, v0
	v_exp_f32_e32 v32, v1
	v_fma_f32 v1, v47, s12, -v212
	v_add_f32_e32 v0, v66, v0
	v_mul_f32_e32 v1, 0x3fb8aa3b, v1
	v_add_f32_e32 v0, v67, v0
	v_exp_f32_e32 v33, v1
	v_fma_f32 v1, v40, s12, -v212
	v_add_f32_e32 v0, v60, v0
	v_mul_f32_e32 v1, 0x3fb8aa3b, v1
	v_add_f32_e32 v0, v61, v0
	v_exp_f32_e32 v34, v1
	v_fma_f32 v1, v41, s12, -v212
	v_add_f32_e32 v0, v62, v0
	v_mul_f32_e32 v1, 0x3fb8aa3b, v1
	v_add_f32_e32 v0, v63, v0
	v_exp_f32_e32 v35, v1
	v_fma_f32 v1, v42, s12, -v212
	v_add_f32_e32 v0, v48, v0
	v_mul_f32_e32 v1, 0x3fb8aa3b, v1
	v_add_f32_e32 v0, v49, v0
	v_exp_f32_e32 v40, v1
	v_fma_f32 v1, v43, s12, -v212
	v_add_f32_e32 v0, v50, v0
	v_mul_f32_e32 v1, 0x3fb8aa3b, v1
	v_add_f32_e32 v0, v51, v0
	v_exp_f32_e32 v41, v1
	v_fma_f32 v1, v36, s12, -v212
	v_add_f32_e32 v0, v52, v0
	v_mul_f32_e32 v1, 0x3fb8aa3b, v1
	v_add_f32_e32 v0, v53, v0
	v_exp_f32_e32 v10, v1
	v_fma_f32 v1, v37, s12, -v212
	v_add_f32_e32 v0, v54, v0
	v_mul_f32_e32 v1, 0x3fb8aa3b, v1
	v_add_f32_e32 v0, v55, v0
	v_exp_f32_e32 v11, v1
	v_fma_f32 v1, v38, s12, -v212
	v_add_f32_e32 v0, v18, v0
	v_mul_f32_e32 v1, 0x3fb8aa3b, v1
	v_add_f32_e32 v0, v19, v0
	v_exp_f32_e32 v12, v1
	v_fma_f32 v1, v39, s12, -v212
	v_add_f32_e32 v0, v32, v0
	v_mul_f32_e32 v1, 0x3fb8aa3b, v1
	v_add_f32_e32 v0, v33, v0
	v_exp_f32_e32 v13, v1
	v_fma_f32 v1, v28, s12, -v212
	v_add_f32_e32 v0, v34, v0
	v_mul_f32_e32 v1, 0x3fb8aa3b, v1
	v_add_f32_e32 v0, v35, v0
	v_exp_f32_e32 v14, v1
	v_fma_f32 v1, v29, s12, -v212
	v_add_f32_e32 v0, v40, v0
	v_mul_f32_e32 v1, 0x3fb8aa3b, v1
	v_add_f32_e32 v0, v41, v0
	v_exp_f32_e32 v15, v1
	v_fma_f32 v1, v30, s12, -v212
	v_add_f32_e32 v0, v10, v0
	v_mul_f32_e32 v1, 0x3fb8aa3b, v1
	v_add_f32_e32 v0, v11, v0
	v_exp_f32_e32 v16, v1
	v_fma_f32 v1, v31, s12, -v212
	v_add_f32_e32 v0, v12, v0
	v_mul_f32_e32 v1, 0x3fb8aa3b, v1
	v_add_f32_e32 v0, v13, v0
	v_exp_f32_e32 v17, v1
	v_add_f32_e32 v0, v14, v0
	v_add_f32_e32 v0, v15, v0
	v_add_f32_e32 v0, v16, v0
	v_add_f32_e32 v1, v17, v0
	v_fma_f32 v0, v24, s12, -v212
	v_mul_f32_e32 v0, 0x3fb8aa3b, v0
	v_exp_f32_e32 v0, v0
	ds_read2_b64 v[28:31], v111 offset1:4
	v_add_f32_e32 v2, v0, v1
	v_fma_f32 v1, v25, s12, -v212
	v_mul_f32_e32 v1, 0x3fb8aa3b, v1
	v_exp_f32_e32 v1, v1
	s_nop 0
	v_add_f32_e32 v3, v1, v2
	v_fma_f32 v2, v26, s12, -v212
	v_mul_f32_e32 v2, 0x3fb8aa3b, v2
	v_exp_f32_e32 v2, v2
	s_nop 0
	v_add_f32_e32 v4, v2, v3
	v_fma_f32 v3, v27, s12, -v212
	v_mul_f32_e32 v3, 0x3fb8aa3b, v3
	v_exp_f32_e32 v3, v3
	s_nop 0
	v_add_f32_e32 v5, v3, v4
	v_fma_f32 v4, v20, s12, -v212
	v_mul_f32_e32 v4, 0x3fb8aa3b, v4
	v_exp_f32_e32 v4, v4
	s_nop 0
	v_add_f32_e32 v6, v4, v5
	v_fma_f32 v5, v21, s12, -v212
	v_mul_f32_e32 v5, 0x3fb8aa3b, v5
	v_exp_f32_e32 v5, v5
	s_nop 0
	v_add_f32_e32 v7, v5, v6
	v_fma_f32 v6, v22, s12, -v212
	v_mul_f32_e32 v6, 0x3fb8aa3b, v6
	v_exp_f32_e32 v6, v6
	s_nop 0
	v_add_f32_e32 v8, v6, v7
	v_fma_f32 v7, v23, s12, -v212
	v_mul_f32_e32 v7, 0x3fb8aa3b, v7
	v_exp_f32_e32 v7, v7
	s_nop 0
	v_add_f32_e32 v8, v7, v8
	ds_bpermute_b32 v9, v210, v8
	s_waitcnt lgkmcnt(0)
	v_add_f32_e32 v8, v8, v9
	ds_bpermute_b32 v9, v211, v8
	s_waitcnt lgkmcnt(0)
	v_add_f32_e32 v8, v8, v9
	v_div_scale_f32 v9, s[0:1], v8, v8, 1.0
	v_rcp_f32_e32 v20, v9
	s_nop 0
	v_fma_f32 v21, -v9, v20, 1.0
	v_fmac_f32_e32 v20, v21, v20
	v_div_scale_f32 v21, vcc, 1.0, v8, 1.0
	v_mul_f32_e32 v22, v21, v20
	v_fma_f32 v23, -v9, v22, v21
	v_fmac_f32_e32 v22, v23, v20
	v_fma_f32 v9, -v9, v22, v21
	v_div_fmas_f32 v9, v9, v20, v22
	v_div_fixup_f32 v8, v9, v8, 1.0
	v_pk_mul_f32 v[20:21], v[136:137], v[8:9] op_sel_hi:[1,0]
	v_pk_mul_f32 v[22:23], v[138:139], v[8:9] op_sel_hi:[1,0]
	v_cvt_pk_bf16_f32 v20, v20, v21
	v_cvt_pk_bf16_f32 v21, v22, v23
	v_pk_mul_f32 v[22:23], v[140:141], v[8:9] op_sel_hi:[1,0]
	v_pk_mul_f32 v[24:25], v[142:143], v[8:9] op_sel_hi:[1,0]
	v_cvt_pk_bf16_f32 v22, v22, v23
	v_cvt_pk_bf16_f32 v23, v24, v25
	ds_read2_b64 v[24:27], v109 offset1:4
	ds_read2_b64 v[36:39], v144 offset1:8
	ds_read2_b64 v[42:45], v145 offset1:8
	ds_read2_b64 v[114:117], v147 offset1:8
	ds_read2_b64 v[136:139], v148 offset1:8
	ds_read2_b64 v[210:213], v149 offset0:8 offset1:12
	ds_read2_b64 v[214:217], v150 offset0:8 offset1:12
	ds_read2_b64 v[218:221], v151 offset1:8
	ds_read2_b64 v[222:225], v152 offset1:8
	s_waitcnt lgkmcnt(7)
	v_mov_b32_e32 v56, v36
	v_mov_b32_e32 v57, v37
	v_pk_mul_f32 v[36:37], v[128:129], v[8:9] op_sel_hi:[1,0]
	s_waitcnt lgkmcnt(1)
	v_mov_b32_e32 v226, v220
	v_mov_b32_e32 v227, v221
	s_waitcnt lgkmcnt(0)
	v_mov_b32_e32 v228, v224
	v_mov_b32_e32 v229, v225
	v_cvt_pk_bf16_f32 v128, v36, v37
	v_pk_mul_f32 v[36:37], v[130:131], v[8:9] op_sel_hi:[1,0]
	v_mfma_f32_16x16x32_bf16 v[224:227], v[226:229], v[20:23], 0
	v_cvt_pk_bf16_f32 v129, v36, v37
	v_pk_mul_f32 v[36:37], v[132:133], v[8:9] op_sel_hi:[1,0]
	ds_read2_b64 v[228:231], v153 offset1:8
	ds_read2_b64 v[232:235], v154 offset1:8
	v_cvt_pk_bf16_f32 v130, v36, v37
	v_pk_mul_f32 v[36:37], v[134:135], v[8:9] op_sel_hi:[1,0]
	ds_read2_b64 v[132:135], v109 offset0:8 offset1:12
	v_pk_mul_f32 v[46:47], v[68:69], v[8:9] op_sel_hi:[1,0]
	v_mov_b32_e32 v58, v42
	v_cvt_pk_bf16_f32 v68, v46, v47
	v_pk_mul_f32 v[46:47], v[70:71], v[8:9] op_sel_hi:[1,0]
	v_mov_b32_e32 v59, v43
	v_cvt_pk_bf16_f32 v69, v46, v47
	v_pk_mul_f32 v[46:47], v[72:73], v[8:9] op_sel_hi:[1,0]
	v_mfma_f32_16x16x32_bf16 v[24:27], v[24:27], v[20:23], 0
	v_cvt_pk_bf16_f32 v70, v46, v47
	v_pk_mul_f32 v[46:47], v[74:75], v[8:9] op_sel_hi:[1,0]
	ds_read2_b64 v[72:75], v109 offset0:16 offset1:20
	v_cvt_pk_bf16_f32 v131, v36, v37
	v_mov_b32_e32 v42, v38
	v_mov_b32_e32 v43, v39
	v_mfma_f32_16x16x32_bf16 v[56:59], v[56:59], v[20:23], 0
	v_cvt_pk_bf16_f32 v71, v46, v47
	v_mov_b32_e32 v140, v114
	v_mov_b32_e32 v141, v115
	s_waitcnt lgkmcnt(1)
	v_mfma_f32_16x16x32_bf16 v[24:27], v[132:135], v[128:131], v[24:27]
	ds_read2_b64 v[132:135], v111 offset0:8 offset1:12
	v_mov_b32_e32 v142, v136
	v_mov_b32_e32 v143, v137
	v_mov_b32_e32 v236, v230
	v_mov_b32_e32 v237, v231
	v_mov_b32_e32 v238, v234
	v_mov_b32_e32 v239, v235
	v_mfma_f32_16x16x32_bf16 v[36:39], v[42:45], v[128:131], v[56:59]
	v_mov_b32_e32 v136, v116
	v_mov_b32_e32 v137, v117
	ds_read2_b64 v[114:117], v150 offset1:4
	ds_read2_b64 v[56:59], v149 offset1:4
	s_waitcnt lgkmcnt(3)
	v_mfma_f32_16x16x32_bf16 v[24:27], v[72:75], v[68:71], v[24:27]
	ds_read2_b64 v[72:75], v111 offset0:16 offset1:20
	v_mov_b32_e32 v220, v222
	v_mov_b32_e32 v221, v223
	v_mfma_f32_16x16x32_bf16 v[28:31], v[28:31], v[20:23], 0
	v_mov_b32_e32 v230, v232
	v_mov_b32_e32 v231, v233
	v_pk_mul_f32 v[46:47], v[64:65], v[8:9] op_sel_hi:[1,0]
	v_mfma_f32_16x16x32_bf16 v[140:143], v[140:143], v[20:23], 0
	v_cvt_pk_bf16_f32 v64, v46, v47
	v_pk_mul_f32 v[46:47], v[66:67], v[8:9] op_sel_hi:[1,0]
	v_pk_mul_f32 v[18:19], v[18:19], v[8:9] op_sel_hi:[1,0]
	v_mfma_f32_16x16x32_bf16 v[210:213], v[210:213], v[20:23], 0
	v_cvt_pk_bf16_f32 v65, v46, v47
	v_pk_mul_f32 v[46:47], v[60:61], v[8:9] op_sel_hi:[1,0]
	v_pk_mul_f32 v[10:11], v[10:11], v[8:9] op_sel_hi:[1,0]
	v_mfma_f32_16x16x32_bf16 v[214:217], v[214:217], v[20:23], 0
	v_cvt_pk_bf16_f32 v66, v46, v47
	v_pk_mul_f32 v[46:47], v[62:63], v[8:9] op_sel_hi:[1,0]
	v_pk_mul_f32 v[12:13], v[12:13], v[8:9] op_sel_hi:[1,0]
	v_mfma_f32_16x16x32_bf16 v[20:23], v[236:239], v[20:23], 0
	v_cvt_pk_bf16_f32 v67, v46, v47
	v_pk_mul_f32 v[46:47], v[48:49], v[8:9] op_sel_hi:[1,0]
	v_pk_mul_f32 v[48:49], v[50:51], v[8:9] op_sel_hi:[1,0]
	s_waitcnt lgkmcnt(3)
	v_mfma_f32_16x16x32_bf16 v[28:31], v[132:135], v[128:131], v[28:31]
	v_cvt_pk_bf16_f32 v46, v46, v47
	v_cvt_pk_bf16_f32 v47, v48, v49
	v_pk_mul_f32 v[48:49], v[52:53], v[8:9] op_sel_hi:[1,0]
	v_mfma_f32_16x16x32_bf16 v[42:45], v[136:139], v[128:131], v[140:143]
	v_mul_f32_e64 v50, v54, v8
	v_mul_f32_e64 v51, v55, v8
	v_cvt_pk_bf16_f32 v48, v48, v49
	v_cvt_pk_bf16_f32 v49, v50, v51
	s_waitcnt lgkmcnt(1)
	v_mfma_f32_16x16x32_bf16 v[56:59], v[56:59], v[128:131], v[210:213]
	v_cvt_pk_bf16_f32 v10, v10, v11
	v_cvt_pk_bf16_f32 v11, v12, v13
	v_pk_mul_f32 v[12:13], v[14:15], v[8:9] op_sel_hi:[1,0]
	v_mfma_f32_16x16x32_bf16 v[114:117], v[114:117], v[128:131], v[214:217]
	v_mul_f32_e64 v14, v16, v8
	v_mul_f32_e64 v15, v17, v8
	v_cvt_pk_bf16_f32 v12, v12, v13
	v_cvt_pk_bf16_f32 v13, v14, v15
	v_mfma_f32_16x16x32_bf16 v[132:135], v[218:221], v[128:131], v[224:227]
	v_mul_f32_e64 v0, v0, v8
	v_mul_f32_e64 v1, v1, v8
	v_pk_mul_f32 v[2:3], v[2:3], v[8:9] op_sel_hi:[1,0]
	v_cvt_pk_bf16_f32 v0, v0, v1
	v_mfma_f32_16x16x32_bf16 v[20:23], v[228:231], v[128:131], v[20:23]
	v_cvt_pk_bf16_f32 v1, v2, v3
	v_pk_mul_f32 v[2:3], v[4:5], v[8:9] op_sel_hi:[1,0]
	v_pk_mul_f32 v[4:5], v[6:7], v[8:9] op_sel_hi:[1,0]
	s_waitcnt lgkmcnt(0)
	v_mfma_f32_16x16x32_bf16 v[28:31], v[72:75], v[68:71], v[28:31]
	ds_read2_b64 v[72:75], v144 offset0:16 offset1:24
	ds_read2_b64 v[128:131], v145 offset0:16 offset1:24
	v_cvt_pk_bf16_f32 v2, v2, v3
	v_cvt_pk_bf16_f32 v3, v4, v5
	s_waitcnt lgkmcnt(1)
	v_mov_b32_e32 v136, v72
	v_mov_b32_e32 v137, v73
	s_waitcnt lgkmcnt(0)
	v_mov_b32_e32 v138, v128
	v_mov_b32_e32 v139, v129
	v_mov_b32_e32 v128, v74
	v_mov_b32_e32 v129, v75
	v_mfma_f32_16x16x32_bf16 v[36:39], v[136:139], v[68:71], v[36:39]
	ds_read2_b64 v[136:139], v147 offset0:16 offset1:24
	ds_read2_b64 v[140:143], v148 offset0:16 offset1:24
	s_waitcnt lgkmcnt(1)
	v_mov_b32_e32 v210, v136
	v_mov_b32_e32 v211, v137
	s_waitcnt lgkmcnt(0)
	v_mov_b32_e32 v212, v140
	v_mov_b32_e32 v213, v141
	v_mov_b32_e32 v140, v138
	v_mov_b32_e32 v141, v139
	v_mfma_f32_16x16x32_bf16 v[42:45], v[210:213], v[68:71], v[42:45]
	ds_read2_b64 v[210:213], v149 offset0:24 offset1:28
	s_waitcnt lgkmcnt(0)
	v_mfma_f32_16x16x32_bf16 v[56:59], v[210:213], v[68:71], v[56:59]
	ds_read2_b64 v[210:213], v150 offset0:24 offset1:28
	s_waitcnt lgkmcnt(0)
	v_mfma_f32_16x16x32_bf16 v[114:117], v[210:213], v[68:71], v[114:117]
	ds_read2_b64 v[210:213], v151 offset0:16 offset1:24
	ds_read2_b64 v[214:217], v152 offset0:16 offset1:24
	s_waitcnt lgkmcnt(1)
	v_mov_b32_e32 v218, v212
	v_mov_b32_e32 v219, v213
	s_waitcnt lgkmcnt(0)
	v_mov_b32_e32 v220, v216
	v_mov_b32_e32 v221, v217
	v_mov_b32_e32 v212, v214
	v_mov_b32_e32 v213, v215
	v_mfma_f32_16x16x32_bf16 v[132:135], v[218:221], v[68:71], v[132:135]
	ds_read2_b64 v[216:219], v153 offset0:16 offset1:24
	ds_read2_b64 v[220:223], v154 offset0:16 offset1:24
	ds_read2_b64 v[60:63], v109 offset0:24 offset1:28
	ds_read2_b64 v[50:53], v109 offset0:32 offset1:36
	s_waitcnt lgkmcnt(1)
	v_mfma_f32_16x16x32_bf16 v[24:27], v[60:63], v[64:67], v[24:27]
	ds_read2_b64 v[60:63], v111 offset0:24 offset1:28
	v_mov_b32_e32 v224, v218
	v_mov_b32_e32 v225, v219
	s_waitcnt lgkmcnt(0)
	v_mfma_f32_16x16x32_bf16 v[28:31], v[60:63], v[64:67], v[28:31]
	ds_read2_b64 v[60:63], v149 offset0:16 offset1:20
	v_mov_b32_e32 v226, v222
	v_mov_b32_e32 v227, v223
	s_waitcnt lgkmcnt(0)
	v_mfma_f32_16x16x32_bf16 v[56:59], v[60:63], v[64:67], v[56:59]
	ds_read2_b64 v[60:63], v150 offset0:16 offset1:20
	v_mov_b32_e32 v218, v220
	v_mov_b32_e32 v219, v221
	v_mfma_f32_16x16x32_bf16 v[24:27], v[50:53], v[46:49], v[24:27]
	ds_read2_b64 v[50:53], v111 offset0:32 offset1:36
	v_mfma_f32_16x16x32_bf16 v[20:23], v[224:227], v[68:71], v[20:23]
	v_mfma_f32_16x16x32_bf16 v[36:39], v[128:131], v[64:67], v[36:39]
	v_mfma_f32_16x16x32_bf16 v[42:45], v[140:143], v[64:67], v[42:45]
	s_waitcnt lgkmcnt(1)
	v_mfma_f32_16x16x32_bf16 v[60:63], v[60:63], v[64:67], v[114:117]
	v_mfma_f32_16x16x32_bf16 v[68:71], v[210:213], v[64:67], v[132:135]
	v_mfma_f32_16x16x32_bf16 v[20:23], v[216:219], v[64:67], v[20:23]
	s_waitcnt lgkmcnt(0)
	v_mfma_f32_16x16x32_bf16 v[28:31], v[50:53], v[46:49], v[28:31]
	ds_read2_b64 v[50:53], v144 offset0:32 offset1:40
	ds_read2_b64 v[64:67], v145 offset0:32 offset1:40
	s_waitcnt lgkmcnt(1)
	v_mov_b32_e32 v72, v50
	v_mov_b32_e32 v73, v51
	s_waitcnt lgkmcnt(0)
	v_mov_b32_e32 v74, v64
	v_mov_b32_e32 v75, v65
	s_nop 1
	v_mfma_f32_16x16x32_bf16 v[36:39], v[72:75], v[46:49], v[36:39]
	ds_read2_b64 v[72:75], v147 offset0:32 offset1:40
	ds_read2_b64 v[114:117], v148 offset0:32 offset1:40
	s_waitcnt lgkmcnt(1)
	v_mov_b32_e32 v128, v72
	v_mov_b32_e32 v129, v73
	s_waitcnt lgkmcnt(0)
	v_mov_b32_e32 v130, v114
	v_mov_b32_e32 v131, v115
	v_mov_b32_e32 v114, v74
	v_mov_b32_e32 v115, v75
	v_mfma_f32_16x16x32_bf16 v[42:45], v[128:131], v[46:49], v[42:45]
	ds_read2_b64 v[128:131], v149 offset0:40 offset1:44
	s_waitcnt lgkmcnt(0)
	v_mfma_f32_16x16x32_bf16 v[54:57], v[128:131], v[46:49], v[56:59]
	ds_read2_b64 v[128:131], v150 offset0:40 offset1:44
	s_waitcnt lgkmcnt(0)
	v_mfma_f32_16x16x32_bf16 v[58:61], v[128:131], v[46:49], v[60:63]
	s_nop 2
	ds_read2_b64 v[62:65], v151 offset0:32 offset1:40
	ds_read2_b64 v[128:131], v152 offset0:32 offset1:40
	s_waitcnt lgkmcnt(1)
	v_mov_b32_e32 v132, v64
	v_mov_b32_e32 v133, v65
	s_waitcnt lgkmcnt(0)
	v_mov_b32_e32 v134, v130
	v_mov_b32_e32 v135, v131
	v_mov_b32_e32 v64, v52
	v_mov_b32_e32 v65, v53
	v_mfma_f32_16x16x32_bf16 v[68:71], v[132:135], v[46:49], v[68:71]
	ds_read2_b64 v[130:133], v153 offset0:32 offset1:40
	ds_read2_b64 v[134:137], v154 offset0:32 offset1:40
	ds_read2_b64 v[14:17], v109 offset0:48 offset1:52
	ds_read2_b64 v[50:53], v150 offset0:32 offset1:36
	s_waitcnt lgkmcnt(3)
	v_mov_b32_e32 v138, v132
	v_mov_b32_e32 v139, v133
	s_waitcnt lgkmcnt(2)
	v_mov_b32_e32 v140, v136
	v_mov_b32_e32 v141, v137
	v_mov_b32_e32 v132, v134
	v_mov_b32_e32 v133, v135
	v_mfma_f32_16x16x32_bf16 v[20:23], v[138:141], v[46:49], v[20:23]
	v_cvt_pk_bf16_f32 v46, v18, v19
	v_pk_mul_f32 v[18:19], v[32:33], v[8:9] op_sel_hi:[1,0]
	s_nop 0
	v_cvt_pk_bf16_f32 v47, v18, v19
	v_pk_mul_f32 v[18:19], v[34:35], v[8:9] op_sel_hi:[1,0]
	ds_read2_b64 v[32:35], v109 offset0:40 offset1:44
	v_cvt_pk_bf16_f32 v48, v18, v19
	v_pk_mul_f32 v[18:19], v[40:41], v[8:9] op_sel_hi:[1,0]
	s_nop 0
	v_cvt_pk_bf16_f32 v49, v18, v19
	s_waitcnt lgkmcnt(0)
	s_nop 0
	v_mfma_f32_16x16x32_bf16 v[24:27], v[32:35], v[46:49], v[24:27]
	ds_read2_b64 v[32:35], v111 offset0:40 offset1:44
	s_waitcnt lgkmcnt(0)
	v_mfma_f32_16x16x32_bf16 v[28:31], v[32:35], v[46:49], v[28:31]
	v_mfma_f32_16x16x32_bf16 v[32:35], v[64:67], v[46:49], v[36:39]
	v_mov_b32_e32 v64, v128
	v_mov_b32_e32 v65, v129
	v_mfma_f32_16x16x32_bf16 v[36:39], v[114:117], v[46:49], v[42:45]
	s_nop 2
	ds_read2_b64 v[40:43], v149 offset0:32 offset1:36
	v_mfma_f32_16x16x32_bf16 v[18:21], v[130:133], v[46:49], v[20:23]
	v_mfma_f32_16x16x32_bf16 v[14:17], v[14:17], v[10:13], v[24:27]
	s_nop 2
	ds_read2_b64 v[22:25], v111 offset0:48 offset1:52
	s_waitcnt lgkmcnt(1)
	v_mfma_f32_16x16x32_bf16 v[40:43], v[40:43], v[46:49], v[54:57]
	v_mfma_f32_16x16x32_bf16 v[50:53], v[50:53], v[46:49], v[58:61]
	v_mfma_f32_16x16x32_bf16 v[54:57], v[62:65], v[46:49], v[68:71]
	ds_read2_b64 v[44:47], v144 offset0:48 offset1:56
	s_nop 0
	ds_read2_b64 v[58:61], v145 offset0:48 offset1:56
	ds_read2_b64 v[62:65], v147 offset0:48 offset1:56
	ds_read2_b64 v[66:69], v148 offset0:48 offset1:56
	s_waitcnt lgkmcnt(3)
	v_mov_b32_e32 v26, v44
	v_mfma_f32_16x16x32_bf16 v[22:25], v[22:25], v[10:13], v[28:31]
	v_mov_b32_e32 v27, v45
	s_waitcnt lgkmcnt(2)
	s_nop 0
	v_mov_b32_e32 v28, v58
	v_mov_b32_e32 v29, v59
	s_nop 1
	v_mfma_f32_16x16x32_bf16 v[32:35], v[26:29], v[10:13], v[32:35]
	s_waitcnt lgkmcnt(1)
	v_mov_b32_e32 v26, v62
	v_mov_b32_e32 v27, v63
	s_waitcnt lgkmcnt(0)
	v_mov_b32_e32 v28, v66
	v_mov_b32_e32 v29, v67
	v_mov_b32_e32 v66, v64
	v_mov_b32_e32 v67, v65
	v_mfma_f32_16x16x32_bf16 v[36:39], v[26:29], v[10:13], v[36:39]
	ds_read2_b64 v[26:29], v149 offset0:56 offset1:60
	s_waitcnt lgkmcnt(0)
	v_mfma_f32_16x16x32_bf16 v[40:43], v[26:29], v[10:13], v[40:43]
	ds_read2_b64 v[26:29], v150 offset0:56 offset1:60
	ds_read2_b64 v[70:73], v151 offset0:48 offset1:56
	ds_read2_b64 v[114:117], v152 offset0:48 offset1:56
	s_waitcnt lgkmcnt(2)
	v_mfma_f32_16x16x32_bf16 v[48:51], v[26:29], v[10:13], v[50:53]
	s_waitcnt lgkmcnt(1)
	v_mov_b32_e32 v26, v72
	v_mov_b32_e32 v27, v73
	s_waitcnt lgkmcnt(0)
	v_mov_b32_e32 v28, v116
	v_mov_b32_e32 v29, v117
	v_mov_b32_e32 v72, v114
	v_mov_b32_e32 v73, v115
	v_mfma_f32_16x16x32_bf16 v[52:55], v[26:29], v[10:13], v[54:57]
	s_nop 2
	ds_read2_b64 v[56:59], v153 offset0:48 offset1:56
	ds_read2_b64 v[128:131], v154 offset0:48 offset1:56
	ds_read2_b64 v[4:7], v109 offset0:56 offset1:60
	s_waitcnt lgkmcnt(2)
	v_mov_b32_e32 v26, v58
	v_mov_b32_e32 v27, v59
	s_waitcnt lgkmcnt(1)
	v_mov_b32_e32 v28, v130
	v_mov_b32_e32 v29, v131
	v_mov_b32_e32 v58, v46
	v_mov_b32_e32 v59, v47
	v_mfma_f32_16x16x32_bf16 v[130:133], v[26:29], v[10:13], v[18:21]
	s_waitcnt lgkmcnt(0)
	v_mfma_f32_16x16x32_bf16 v[28:31], v[4:7], v[0:3], v[14:17]
	ds_read2_b64 v[4:7], v111 offset0:56 offset1:60
	s_waitcnt lgkmcnt(0)
	v_mfma_f32_16x16x32_bf16 v[24:27], v[4:7], v[0:3], v[22:25]
	ds_read2_b64 v[4:7], v149 offset0:48 offset1:52
	s_waitcnt lgkmcnt(0)
	v_mfma_f32_16x16x32_bf16 v[12:15], v[4:7], v[0:3], v[40:43]
	ds_read2_b64 v[4:7], v150 offset0:48 offset1:52
	v_mfma_f32_16x16x32_bf16 v[20:23], v[58:61], v[0:3], v[32:35]
	v_mov_b32_e32 v58, v128
	v_mov_b32_e32 v59, v129
	v_mfma_f32_16x16x32_bf16 v[16:19], v[66:69], v[0:3], v[36:39]
	s_waitcnt lgkmcnt(0)
	v_mfma_f32_16x16x32_bf16 v[8:11], v[4:7], v[0:3], v[48:51]
	v_mfma_f32_16x16x32_bf16 v[4:7], v[70:73], v[0:3], v[52:55]
	v_mfma_f32_16x16x32_bf16 v[0:3], v[56:59], v[0:3], v[130:133]
	s_mov_b64 s[0:1], exec
	v_readlane_b32 s14, v255, 47
	v_readlane_b32 s15, v255, 48
	s_and_b64 s[14:15], s[0:1], s[14:15]
	s_mov_b64 exec, s[14:15]
	s_cbranch_execz .LBB0_1843
	v_bfe_u32 v34, v28, 16, 1
	v_add3_u32 v28, v28, v34, s90
	v_bfe_u32 v34, v29, 16, 1
	v_lshrrev_b32_e32 v28, 16, v28
	v_add3_u32 v29, v29, v34, s90
	s_lshl_b32 s16, s33, 7
	v_mov_b64_e32 v[32:33], s[38:39]
	v_and_or_b32 v28, v29, s87, v28
	v_bfe_u32 v29, v30, 16, 1
	v_mad_u64_u32 v[32:33], s[14:15], v78, s97, v[32:33]
	s_lshl_b32 s78, s16, 1
	v_add3_u32 v29, v30, v29, s90
	v_bfe_u32 v30, v31, 16, 1
	v_lshl_add_u64 v[32:33], v[32:33], 0, s[78:79]
	v_lshrrev_b32_e32 v29, 16, v29
	v_add3_u32 v30, v31, v30, s90
	v_lshl_add_u64 v[32:33], v[88:89], 1, v[32:33]
	v_and_or_b32 v29, v30, s87, v29
	global_store_dwordx2 v[32:33], v[28:29], off offset:2048
	v_bfe_u32 v28, v24, 16, 1
	v_add3_u32 v24, v24, v28, s90
	v_bfe_u32 v28, v25, 16, 1
	v_lshrrev_b32_e32 v24, 16, v24
	v_add3_u32 v25, v25, v28, s90
	v_and_or_b32 v24, v25, s87, v24
	v_bfe_u32 v25, v26, 16, 1
	v_add3_u32 v25, v26, v25, s90
	v_bfe_u32 v26, v27, 16, 1
	v_lshrrev_b32_e32 v25, 16, v25
	v_add3_u32 v26, v27, v26, s90
	v_and_or_b32 v25, v26, s87, v25
	global_store_dwordx2 v[32:33], v[24:25], off offset:2080
	v_bfe_u32 v24, v20, 16, 1
	v_add3_u32 v20, v20, v24, s90
	v_bfe_u32 v24, v21, 16, 1
	v_lshrrev_b32_e32 v20, 16, v20
	v_add3_u32 v21, v21, v24, s90
	v_and_or_b32 v20, v21, s87, v20
	v_bfe_u32 v21, v22, 16, 1
	v_add3_u32 v21, v22, v21, s90
	v_bfe_u32 v22, v23, 16, 1
	v_lshrrev_b32_e32 v21, 16, v21
	v_add3_u32 v22, v23, v22, s90
	v_and_or_b32 v21, v22, s87, v21
	global_store_dwordx2 v[32:33], v[20:21], off offset:2112
	v_bfe_u32 v20, v16, 16, 1
	v_add3_u32 v16, v16, v20, s90
	v_bfe_u32 v20, v17, 16, 1
	v_lshrrev_b32_e32 v16, 16, v16
	v_add3_u32 v17, v17, v20, s90
	v_and_or_b32 v16, v17, s87, v16
	v_bfe_u32 v17, v18, 16, 1
	v_add3_u32 v17, v18, v17, s90
	v_bfe_u32 v18, v19, 16, 1
	v_lshrrev_b32_e32 v17, 16, v17
	v_add3_u32 v18, v19, v18, s90
	v_and_or_b32 v17, v18, s87, v17
	global_store_dwordx2 v[32:33], v[16:17], off offset:2144
	v_bfe_u32 v16, v12, 16, 1
	v_add3_u32 v12, v12, v16, s90
	v_bfe_u32 v16, v13, 16, 1
	v_lshrrev_b32_e32 v12, 16, v12
	v_add3_u32 v13, v13, v16, s90
	v_and_or_b32 v12, v13, s87, v12
	v_bfe_u32 v13, v14, 16, 1
	v_add3_u32 v13, v14, v13, s90
	v_bfe_u32 v14, v15, 16, 1
	v_lshrrev_b32_e32 v13, 16, v13
	v_add3_u32 v14, v15, v14, s90
	v_and_or_b32 v13, v14, s87, v13
	global_store_dwordx2 v[32:33], v[12:13], off offset:2176
	v_bfe_u32 v12, v8, 16, 1
	v_add3_u32 v8, v8, v12, s90
	v_bfe_u32 v12, v9, 16, 1
	v_lshrrev_b32_e32 v8, 16, v8
	v_add3_u32 v9, v9, v12, s90
	v_and_or_b32 v8, v9, s87, v8
	v_bfe_u32 v9, v10, 16, 1
	v_add3_u32 v9, v10, v9, s90
	v_bfe_u32 v10, v11, 16, 1
	v_lshrrev_b32_e32 v9, 16, v9
	v_add3_u32 v10, v11, v10, s90
	v_and_or_b32 v9, v10, s87, v9
	global_store_dwordx2 v[32:33], v[8:9], off offset:2208
	v_bfe_u32 v8, v4, 16, 1
	v_add3_u32 v4, v4, v8, s90
	v_bfe_u32 v8, v5, 16, 1
	v_lshrrev_b32_e32 v4, 16, v4
	v_add3_u32 v5, v5, v8, s90
	v_and_or_b32 v4, v5, s87, v4
	v_bfe_u32 v5, v6, 16, 1
	v_add3_u32 v5, v6, v5, s90
	v_bfe_u32 v6, v7, 16, 1
	v_lshrrev_b32_e32 v5, 16, v5
	v_add3_u32 v6, v7, v6, s90
	v_and_or_b32 v5, v6, s87, v5
	global_store_dwordx2 v[32:33], v[4:5], off offset:2240
	v_bfe_u32 v4, v0, 16, 1
	v_add3_u32 v0, v0, v4, s90
	v_bfe_u32 v4, v1, 16, 1
	v_lshrrev_b32_e32 v0, 16, v0
	v_add3_u32 v1, v1, v4, s90
	v_and_or_b32 v0, v1, s87, v0
	v_bfe_u32 v1, v2, 16, 1
	v_add3_u32 v1, v2, v1, s90
	v_bfe_u32 v2, v3, 16, 1
	v_lshrrev_b32_e32 v1, 16, v1
	v_add3_u32 v2, v3, v2, s90
	v_and_or_b32 v1, v2, s87, v1
	global_store_dwordx2 v[32:33], v[0:1], off offset:2272
